# v62 + permlane-swap reductions in prompt attention + SSD causal-mask decay values preloaded once per chunk (no dependent LDS read inside each mask block)
# speedup vs baseline: 1.0105x; 1.0056x over previous
; DI f32x4 mfma16(bf16x8 a, bf16x8 b, f32x4 c) { return __builtin_amdgcn_mfma_f32_16x16x32_bf16(a, b, c, 0, 0, 0); }
; PH void attn_prompt_item(const Params& p, int layer, int item) {
;     ...
;     for (int qt = 0; qt < 2; ++qt) {
;       const int qi = q0 + qt * 16 + l15;
;       const int tpos = nb * 128 + qi;
;       float own[8], o1[8];
;       unpack8v(cq[qt][0], own);
;       unpack8v(cq[qt][1], o1);
;       if (quad < 2) {
;         float pr[8];
;         unpack8v(cq[qt][2], pr);
;         const float* cs = ROPE + (size_t)tpos * 16;
;         const float sg = (quad == 0) ? -1.f : 1.f;
; #pragma unroll
;         for (int i = 0; i < 8; ++i) own[i] = own[i] * cs[2 * i] + sg * pr[i] * cs[2 * i + 1];
;       }
; #pragma unroll
;       for (int i = 0; i < 8; ++i) { own[i] *= 0.125f; o1[i] *= 0.125f; }
;       qf[qt][0] = __builtin_bit_cast(bf16x8, pack8(own));
;       qf[qt][1] = __builtin_bit_cast(bf16x8, pack8(o1));
;     }
;     f32x4 s[10][2];
; #pragma unroll
;     for (int kt = 0; kt < 10; ++kt) { s[kt][0] = (f32x4){0.f, 0.f, 0.f, 0.f}; s[kt][1] = (f32x4){0.f, 0.f, 0.f, 0.f}; }
; #pragma unroll
;     for (int ks = 0; ks < 2; ++ks)
; #pragma unroll
;       for (int kt = 0; kt < 10; ++kt) {
;         const bf16x8 af = ldfrag(Ks, 72, q0 + kt * 16, ks * 32, lane);
;         s[kt][0] = mfma16(af, qf[0][ks], s[kt][0]);
;         s[kt][1] = mfma16(af, qf[1][ks], s[kt][1]);
;       }
.LBB0_281:
	s_or_b64 exec, exec, s[0:1]
	s_waitcnt vmcnt(14)
	v_lshlrev_b32_e32 v32, 16, v28
	v_and_b32_e32 v33, 0xffff0000, v28
	v_lshlrev_b32_e32 v28, 16, v29
	v_and_b32_e32 v29, 0xffff0000, v29
	v_lshlrev_b32_e32 v34, 16, v30
	v_and_b32_e32 v35, 0xffff0000, v30
	v_lshlrev_b32_e32 v30, 16, v31
	v_and_b32_e32 v31, 0xffff0000, v31
	v_pk_mul_f32 v[38:39], v[32:33], s[26:27] op_sel_hi:[1,0]
	v_pk_mul_f32 v[32:33], v[50:51], s[26:27] op_sel_hi:[1,0]
	v_pk_mul_f32 v[50:51], v[28:29], s[26:27] op_sel_hi:[1,0]
	v_pk_mul_f32 v[28:29], v[48:49], s[26:27] op_sel_hi:[1,0]
	v_pk_mul_f32 v[48:49], v[34:35], s[26:27] op_sel_hi:[1,0]
	v_pk_mul_f32 v[34:35], v[46:47], s[26:27] op_sel_hi:[1,0]
	v_pk_mul_f32 v[46:47], v[30:31], s[26:27] op_sel_hi:[1,0]
	v_pk_mul_f32 v[30:31], v[44:45], s[26:27] op_sel_hi:[1,0]
	v_cvt_pk_bf16_f32 v32, v32, v33
	v_cvt_pk_bf16_f32 v33, v28, v29
	v_cvt_pk_bf16_f32 v28, v38, v39
	v_lshlrev_b32_e32 v38, 16, v24
	v_and_b32_e32 v39, 0xffff0000, v24
	v_lshlrev_b32_e32 v24, 16, v25
	v_and_b32_e32 v25, 0xffff0000, v25
	v_lshlrev_b32_e32 v44, 16, v26
	v_and_b32_e32 v45, 0xffff0000, v26
	v_lshlrev_b32_e32 v26, 16, v27
	v_and_b32_e32 v27, 0xffff0000, v27
	v_or_b32_e32 v163, s7, v119
	v_cvt_pk_bf16_f32 v34, v34, v35
	v_cvt_pk_bf16_f32 v35, v30, v31
	v_cvt_pk_bf16_f32 v30, v48, v49
	v_cvt_pk_bf16_f32 v31, v46, v47
	v_pk_mul_f32 v[46:47], v[38:39], s[26:27] op_sel_hi:[1,0]
	v_pk_mul_f32 v[38:39], v[54:55], s[26:27] op_sel_hi:[1,0]
	v_pk_mul_f32 v[48:49], v[24:25], s[26:27] op_sel_hi:[1,0]
	v_pk_mul_f32 v[24:25], v[42:43], s[26:27] op_sel_hi:[1,0]
	v_pk_mul_f32 v[42:43], v[44:45], s[26:27] op_sel_hi:[1,0]
	v_pk_mul_f32 v[40:41], v[40:41], s[26:27] op_sel_hi:[1,0]
	v_pk_mul_f32 v[44:45], v[26:27], s[26:27] op_sel_hi:[1,0]
	v_pk_mul_f32 v[26:27], v[36:37], s[26:27] op_sel_hi:[1,0]
	v_mad_u64_u32 v[150:151], s[0:1], v163, s11, v[118:119]
	v_cvt_pk_bf16_f32 v29, v50, v51
	v_cvt_pk_bf16_f32 v36, v38, v39
	v_cvt_pk_bf16_f32 v37, v24, v25
	v_cvt_pk_bf16_f32 v38, v40, v41
	v_cvt_pk_bf16_f32 v39, v26, v27
	v_cvt_pk_bf16_f32 v25, v48, v49
	v_cvt_pk_bf16_f32 v26, v42, v43
	ds_read_b128 v[40:43], v150
	ds_read_b128 v[48:51], v150 offset:2304
	s_waitcnt lgkmcnt(0)
	v_mfma_f32_16x16x32_bf16 v[104:107], v[48:51], v[32:35], 0
	ds_read_b128 v[52:55], v150 offset:6912
	ds_read_b128 v[76:79], v150 offset:18432
	ds_read_b128 v[108:111], v150 offset:20736
	v_mfma_f32_16x16x32_bf16 v[164:167], v[48:51], v[36:39], 0
	ds_read_b128 v[48:51], v150 offset:4608
	v_cvt_pk_bf16_f32 v24, v46, v47
	v_cvt_pk_bf16_f32 v27, v44, v45
	s_waitcnt lgkmcnt(0)
	v_mfma_f32_16x16x32_bf16 v[56:59], v[48:51], v[32:35], 0
	s_movk_i32 s13, 0x5e
	v_or_b32_e32 v133, 16, v163
	v_mfma_f32_16x16x32_bf16 v[96:99], v[48:51], v[36:39], 0
	v_mfma_f32_16x16x32_bf16 v[48:51], v[52:55], v[32:35], 0
	v_mfma_f32_16x16x32_bf16 v[88:91], v[52:55], v[36:39], 0
	ds_read_b128 v[52:55], v150 offset:9216
	s_waitcnt lgkmcnt(0)
	v_mfma_f32_16x16x32_bf16 v[60:63], v[52:55], v[32:35], 0
	v_mfma_f32_16x16x32_bf16 v[92:95], v[52:55], v[36:39], 0
	ds_read_b128 v[52:55], v150 offset:11520
	s_waitcnt lgkmcnt(0)
	v_mfma_f32_16x16x32_bf16 v[64:67], v[52:55], v[32:35], 0
	v_mfma_f32_16x16x32_bf16 v[84:87], v[52:55], v[36:39], 0
	ds_read_b128 v[52:55], v150 offset:13824
	s_waitcnt lgkmcnt(0)
	v_mfma_f32_16x16x32_bf16 v[68:71], v[52:55], v[32:35], 0
	v_mfma_f32_16x16x32_bf16 v[100:103], v[52:55], v[36:39], 0
	ds_read_b128 v[52:55], v150 offset:16128
	v_mfma_f32_16x16x32_bf16 v[44:47], v[40:43], v[32:35], 0
	v_mfma_f32_16x16x32_bf16 v[40:43], v[40:43], v[36:39], 0
	s_waitcnt lgkmcnt(0)
	v_mfma_f32_16x16x32_bf16 v[72:75], v[52:55], v[32:35], 0
	v_mfma_f32_16x16x32_bf16 v[80:83], v[52:55], v[36:39], 0
	v_mfma_f32_16x16x32_bf16 v[52:55], v[76:79], v[32:35], 0
	v_mfma_f32_16x16x32_bf16 v[76:79], v[76:79], v[36:39], 0
	v_mfma_f32_16x16x32_bf16 v[32:35], v[108:111], v[32:35], 0
	v_mfma_f32_16x16x32_bf16 v[36:39], v[108:111], v[36:39], 0
	ds_read_b128 v[108:111], v150 offset:64
	s_waitcnt lgkmcnt(0)
	v_mfma_f32_16x16x32_bf16 v[112:115], v[108:111], v[28:31], v[44:47]
	s_nop 2
	ds_read_b128 v[44:47], v150 offset:2368
	v_mfma_f32_16x16x32_bf16 v[40:43], v[108:111], v[24:27], v[40:43]
	s_waitcnt lgkmcnt(0)
	v_mfma_f32_16x16x32_bf16 v[108:111], v[44:47], v[28:31], v[104:107]
	v_mfma_f32_16x16x32_bf16 v[44:47], v[44:47], v[24:27], v[164:167]
	s_nop 2
	ds_read_b128 v[164:167], v150 offset:4672
	s_waitcnt lgkmcnt(0)
	v_mfma_f32_16x16x32_bf16 v[104:107], v[164:167], v[28:31], v[56:59]
	s_nop 1
	v_cndmask_b32_e64 v44, v191, v44, s[40:41]
	v_mfma_f32_16x16x32_bf16 v[56:59], v[164:167], v[24:27], v[96:99]
	ds_read_b128 v[164:167], v150 offset:6976
	s_waitcnt lgkmcnt(0)
	v_mfma_f32_16x16x32_bf16 v[96:99], v[164:167], v[28:31], v[48:51]
	v_mfma_f32_16x16x32_bf16 v[48:51], v[164:167], v[24:27], v[88:91]
	ds_read_b128 v[164:167], v150 offset:9280
	s_waitcnt lgkmcnt(0)
	v_mfma_f32_16x16x32_bf16 v[88:91], v[164:167], v[28:31], v[60:63]
	v_mfma_f32_16x16x32_bf16 v[60:63], v[164:167], v[24:27], v[92:95]
	ds_read_b128 v[164:167], v150 offset:11584
	s_waitcnt lgkmcnt(0)
	v_mfma_f32_16x16x32_bf16 v[92:95], v[164:167], v[28:31], v[64:67]
	v_mfma_f32_16x16x32_bf16 v[64:67], v[164:167], v[24:27], v[84:87]
	ds_read_b128 v[164:167], v150 offset:13888
	s_waitcnt lgkmcnt(0)
	v_mfma_f32_16x16x32_bf16 v[84:87], v[164:167], v[28:31], v[68:71]
	v_mfma_f32_16x16x32_bf16 v[68:71], v[164:167], v[24:27], v[100:103]
	ds_read_b128 v[164:167], v150 offset:16192
	s_waitcnt lgkmcnt(0)
	v_mfma_f32_16x16x32_bf16 v[100:103], v[164:167], v[28:31], v[72:75]
	v_mfma_f32_16x16x32_bf16 v[72:75], v[164:167], v[24:27], v[80:83]
	s_nop 2
	ds_read_b128 v[80:83], v150 offset:18496
	s_waitcnt lgkmcnt(0)
; DI f32x4 mfma16(bf16x8 a, bf16x8 b, f32x4 c) { return __builtin_amdgcn_mfma_f32_16x16x32_bf16(a, b, c, 0, 0, 0); }
; PH void attn_prompt_item(const Params& p, int layer, int item) {
;     ...
; #pragma unroll
;     for (int ks = 0; ks < 2; ++ks)
; #pragma unroll
;       for (int kt = 0; kt < 10; ++kt) {
;         const bf16x8 af = ldfrag(Ks, 72, q0 + kt * 16, ks * 32, lane);
;         s[kt][0] = mfma16(af, qf[0][ks], s[kt][0]);
;         s[kt][1] = mfma16(af, qf[1][ks], s[kt][1]);
;       }
;     float inv[2];
;     bf16x8 pf[5][2];
; #pragma unroll
;     for (int qt = 0; qt < 2; ++qt) {
;       const int i = q0 + qt * 16 + l15;
;       float mx = -INFINITY;
; #pragma unroll
;       for (int kt = 0; kt < 10; ++kt)
; #pragma unroll
;         for (int r = 0; r < 4; ++r) {
;           const int j = q0 + kt * 16 + quad * 4 + r;
;           const bool valid = (j >= i) && (j <= i + 128) && (nb > 0 || j >= 128);
;           const float v = valid ? s[kt][qt][r] : -INFINITY;
;           s[kt][qt][r] = v;
;           mx = fmaxf(mx, v);
;         }
	v_mfma_f32_16x16x32_bf16 v[52:55], v[80:83], v[28:31], v[52:55]
	s_nop 7
	v_cndmask_b32_e64 v52, v52, v191, s[42:43]
	v_mfma_f32_16x16x32_bf16 v[76:79], v[80:83], v[24:27], v[76:79]
	ds_read_b128 v[80:83], v150 offset:20800
	v_or_b32_e32 v150, s7, v155
	v_add_u32_e32 v151, 0x70, v150
	s_waitcnt lgkmcnt(0)
	v_mfma_f32_16x16x32_bf16 v[28:31], v[80:83], v[28:31], v[32:35]
	s_nop 2
	v_or_b32_e32 v34, 16, v150
	v_add_u32_e32 v164, 0x82, v150
	v_add_u32_e32 v165, 0x83, v150
	v_mfma_f32_16x16x32_bf16 v[80:83], v[80:83], v[24:27], v[36:39]
	v_cndmask_b32_e64 v25, v191, v112, s[40:41]
	v_or_b32_e32 v112, 1, v150
	v_cmp_ge_u32_e32 vcc, v112, v163
	s_and_b64 vcc, s[44:45], vcc
	v_or_b32_e32 v24, 0x80, v163
	v_cndmask_b32_e32 v26, v191, v113, vcc
	v_or_b32_e32 v113, 2, v150
	v_cmp_ge_u32_e32 vcc, v113, v163
	s_and_b64 vcc, s[44:45], vcc
	v_max3_f32 v27, v25, s96, v26
	v_cndmask_b32_e32 v32, v191, v114, vcc
	v_or_b32_e32 v114, 3, v150
	v_cmp_ge_u32_e32 vcc, v114, v163
	s_and_b64 vcc, s[44:45], vcc
	v_add_u32_e32 v166, 0x90, v150
	v_cndmask_b32_e32 v33, v191, v115, vcc
	v_cmp_ge_u32_e32 vcc, v34, v163
	s_and_b64 vcc, s[44:45], vcc
	v_add_u32_e32 v115, 0x61, v150
	v_cndmask_b32_e32 v34, v191, v108, vcc
	v_or_b32_e32 v108, 17, v150
	v_cmp_ge_u32_e32 vcc, v108, v163
	s_and_b64 vcc, s[44:45], vcc
	v_max3_f32 v27, v27, v32, v33
	v_cndmask_b32_e32 v35, v191, v109, vcc
	v_or_b32_e32 v109, 18, v150
	v_cmp_ge_u32_e32 vcc, v109, v163
	s_and_b64 vcc, s[44:45], vcc
	v_max3_f32 v27, v27, v34, v35
	v_cndmask_b32_e32 v36, v191, v110, vcc
	v_or_b32_e32 v110, 19, v150
	v_cmp_ge_u32_e32 vcc, v110, v163
	s_and_b64 vcc, s[44:45], vcc
	v_add_u32_e32 v167, 0x91, v150
	v_cndmask_b32_e32 v37, v191, v111, vcc
	v_add_u32_e32 v111, 32, v150
	v_cmp_ge_u32_e32 vcc, v111, v163
	v_cmp_le_u32_e64 s[0:1], v111, v24
	s_and_b64 s[0:1], vcc, s[0:1]
	s_cmp_gt_u32 s15, 2
	s_cselect_b64 s[8:9], -1, 0
	s_or_b64 s[8:9], s[44:45], s[8:9]
	s_and_b64 vcc, s[0:1], s[8:9]
	v_cndmask_b32_e32 v38, v191, v104, vcc
	v_add_u32_e32 v104, 33, v150
	v_cmp_ge_u32_e32 vcc, v104, v163
	v_cmp_le_u32_e64 s[0:1], v104, v24
	s_and_b64 s[0:1], vcc, s[0:1]
	v_cmp_lt_u32_e32 vcc, s13, v150
	s_or_b64 s[46:47], s[44:45], vcc
	s_and_b64 vcc, s[0:1], s[46:47]
	v_cndmask_b32_e32 v39, v191, v105, vcc
	v_add_u32_e32 v105, 34, v150
	v_cmp_ge_u32_e32 vcc, v105, v163
	v_cmp_le_u32_e64 s[0:1], v105, v24
	s_movk_i32 s13, 0x5d
	s_and_b64 s[0:1], vcc, s[0:1]
	v_cmp_lt_u32_e32 vcc, s13, v150
	s_or_b64 s[50:51], s[44:45], vcc
	s_and_b64 vcc, s[0:1], s[50:51]
	v_cndmask_b32_e32 v170, v191, v106, vcc
	v_add_u32_e32 v106, 35, v150
	v_cmp_ge_u32_e32 vcc, v106, v163
	v_cmp_le_u32_e64 s[0:1], v106, v24
	s_movk_i32 s13, 0x5c
	s_and_b64 s[0:1], vcc, s[0:1]
	v_cmp_lt_u32_e32 vcc, s13, v150
	s_or_b64 s[52:53], s[44:45], vcc
	s_and_b64 vcc, s[0:1], s[52:53]
	v_cndmask_b32_e32 v171, v191, v107, vcc
	v_add_u32_e32 v107, 48, v150
	v_cmp_ge_u32_e32 vcc, v107, v163
	v_cmp_le_u32_e64 s[0:1], v107, v24
	s_and_b64 s[0:1], vcc, s[0:1]
	s_and_b64 vcc, s[0:1], s[8:9]
	v_cndmask_b32_e32 v172, v191, v96, vcc
	v_add_u32_e32 v96, 49, v150
	v_cmp_ge_u32_e32 vcc, v96, v163
	v_cmp_le_u32_e64 s[0:1], v96, v24
	s_movk_i32 s13, 0x4e
	s_and_b64 s[0:1], vcc, s[0:1]
	v_cmp_lt_u32_e32 vcc, s13, v150
	s_or_b64 s[54:55], s[44:45], vcc
	s_and_b64 vcc, s[0:1], s[54:55]
	v_cndmask_b32_e32 v173, v191, v97, vcc
	v_add_u32_e32 v97, 50, v150
	v_cmp_ge_u32_e32 vcc, v97, v163
	v_cmp_le_u32_e64 s[0:1], v97, v24
	s_movk_i32 s13, 0x4d
	s_and_b64 s[0:1], vcc, s[0:1]
	v_cmp_lt_u32_e32 vcc, s13, v150
	s_or_b64 s[56:57], s[44:45], vcc
	s_and_b64 vcc, s[0:1], s[56:57]
	v_cndmask_b32_e32 v174, v191, v98, vcc
	v_add_u32_e32 v98, 51, v150
	v_cmp_ge_u32_e32 vcc, v98, v163
	v_cmp_le_u32_e64 s[0:1], v98, v24
	s_movk_i32 s13, 0x4c
	s_and_b64 s[0:1], vcc, s[0:1]
	v_cmp_lt_u32_e32 vcc, s13, v150
	s_or_b64 s[58:59], s[44:45], vcc
	s_and_b64 vcc, s[0:1], s[58:59]
	v_cndmask_b32_e32 v175, v191, v99, vcc
	v_add_u32_e32 v99, 64, v150
	v_cmp_ge_u32_e32 vcc, v99, v163
	v_cmp_le_u32_e64 s[0:1], v99, v24
	s_and_b64 s[0:1], vcc, s[0:1]
	s_cmp_gt_u32 s15, 1
	s_cselect_b64 s[18:19], -1, 0
	s_or_b64 s[48:49], s[44:45], s[18:19]
	s_and_b64 vcc, s[0:1], s[48:49]
	v_cndmask_b32_e32 v176, v191, v88, vcc
	v_add_u32_e32 v88, 0x41, v150
	v_cmp_ge_u32_e32 vcc, v88, v163
	v_cmp_le_u32_e64 s[0:1], v88, v24
	s_and_b64 s[0:1], vcc, s[0:1]
	v_cmp_lt_u32_e32 vcc, 62, v150
	s_or_b64 s[62:63], s[44:45], vcc
	s_and_b64 vcc, s[0:1], s[62:63]
	v_cndmask_b32_e32 v177, v191, v89, vcc
	v_add_u32_e32 v89, 0x42, v150
	v_cmp_ge_u32_e32 vcc, v89, v163
	v_cmp_le_u32_e64 s[0:1], v89, v24
	s_and_b64 s[0:1], vcc, s[0:1]
	v_cmp_lt_u32_e32 vcc, 61, v150
	s_or_b64 s[64:65], s[44:45], vcc
	s_and_b64 vcc, s[0:1], s[64:65]
	v_cndmask_b32_e32 v178, v191, v90, vcc
	v_add_u32_e32 v90, 0x43, v150
	v_cmp_ge_u32_e32 vcc, v90, v163
	v_cmp_le_u32_e64 s[0:1], v90, v24
	s_and_b64 s[0:1], vcc, s[0:1]
	v_cmp_lt_u32_e32 vcc, 60, v150
	s_or_b64 s[66:67], s[44:45], vcc
	s_and_b64 vcc, s[0:1], s[66:67]
	v_cndmask_b32_e32 v179, v191, v91, vcc
	v_add_u32_e32 v91, 0x50, v150
	v_cmp_ge_u32_e32 vcc, v91, v163
	v_cmp_le_u32_e64 s[0:1], v91, v24
	s_and_b64 s[0:1], vcc, s[0:1]
	s_and_b64 vcc, s[0:1], s[48:49]
	v_cndmask_b32_e32 v180, v191, v92, vcc
	v_add_u32_e32 v92, 0x51, v150
	v_cmp_ge_u32_e32 vcc, v92, v163
	v_cmp_le_u32_e64 s[0:1], v92, v24
	s_and_b64 s[0:1], vcc, s[0:1]
	v_cmp_lt_u32_e32 vcc, 46, v150
	s_or_b64 s[68:69], s[44:45], vcc
	s_and_b64 vcc, s[0:1], s[68:69]
	v_cndmask_b32_e32 v181, v191, v93, vcc
	v_add_u32_e32 v93, 0x52, v150
	v_cmp_ge_u32_e32 vcc, v93, v163
	v_cmp_le_u32_e64 s[0:1], v93, v24
	s_and_b64 s[0:1], vcc, s[0:1]
	v_cmp_lt_u32_e32 vcc, 45, v150
; PH void attn_prompt_item(const Params& p, int layer, int item) {
;     ...
;       float mx = -INFINITY;
; #pragma unroll
;       for (int kt = 0; kt < 10; ++kt)
; #pragma unroll
;         for (int r = 0; r < 4; ++r) {
;           const int j = q0 + kt * 16 + quad * 4 + r;
;           const bool valid = (j >= i) && (j <= i + 128) && (nb > 0 || j >= 128);
;           const float v = valid ? s[kt][qt][r] : -INFINITY;
;           s[kt][qt][r] = v;
;           mx = fmaxf(mx, v);
;         }
;       mx = fmaxf(mx, __shfl_xor(mx, 16));
;       mx = fmaxf(mx, __shfl_xor(mx, 32));
;       mx = fmaxf(mx, sink);
;       float sum = 0.f;
; #pragma unroll
;       for (int kt = 0; kt < 10; ++kt)
; #pragma unroll
;         for (int r = 0; r < 4; ++r) {
;           const float e = __expf(s[kt][qt][r] - mx);
;           s[kt][qt][r] = e;
;           sum += e;
	s_or_b64 s[70:71], s[44:45], vcc
	s_and_b64 vcc, s[0:1], s[70:71]
	v_cndmask_b32_e32 v203, v191, v94, vcc
	v_add_u32_e32 v94, 0x53, v150
	v_cmp_ge_u32_e32 vcc, v94, v163
	v_cmp_le_u32_e64 s[0:1], v94, v24
	s_and_b64 s[0:1], vcc, s[0:1]
	v_cmp_lt_u32_e32 vcc, 44, v150
	s_or_b64 s[72:73], s[44:45], vcc
	s_and_b64 vcc, s[0:1], s[72:73]
	v_cndmask_b32_e32 v204, v191, v95, vcc
	v_add_u32_e32 v95, 0x60, v150
	v_cmp_ge_u32_e32 vcc, v95, v163
	v_cmp_le_u32_e64 s[0:1], v95, v24
	s_and_b64 s[0:1], vcc, s[0:1]
	s_or_b32 s13, s15, s6
	s_cmp_lg_u32 s13, 0
	s_cselect_b64 s[60:61], -1, 0
	s_and_b64 vcc, s[60:61], s[0:1]
	v_cndmask_b32_e32 v84, v191, v84, vcc
	v_cmp_ge_u32_e32 vcc, v115, v163
	v_cmp_le_u32_e64 s[0:1], v115, v24
	s_and_b64 s[0:1], vcc, s[0:1]
	v_cmp_lt_u32_e32 vcc, 30, v150
	s_or_b64 s[74:75], s[44:45], vcc
	s_and_b64 vcc, s[0:1], s[74:75]
	v_cndmask_b32_e32 v205, v191, v85, vcc
	v_add_u32_e32 v85, 0x62, v150
	v_cmp_ge_u32_e32 vcc, v85, v163
	v_cmp_le_u32_e64 s[0:1], v85, v24
	s_and_b64 s[0:1], vcc, s[0:1]
	v_cmp_lt_u32_e32 vcc, 29, v150
	s_or_b64 s[76:77], s[44:45], vcc
	s_and_b64 vcc, s[0:1], s[76:77]
	v_cndmask_b32_e32 v206, v191, v86, vcc
	v_add_u32_e32 v86, 0x63, v150
	v_cmp_ge_u32_e32 vcc, v86, v163
	v_cmp_le_u32_e64 s[0:1], v86, v24
	s_and_b64 s[0:1], vcc, s[0:1]
	v_cmp_lt_u32_e32 vcc, 28, v150
	s_or_b64 s[78:79], s[44:45], vcc
	s_and_b64 vcc, s[0:1], s[78:79]
	v_cndmask_b32_e32 v207, v191, v87, vcc
	v_cmp_le_u32_e32 vcc, v151, v24
	v_max3_f32 v27, v27, v36, v37
	s_and_b64 vcc, s[60:61], vcc
	v_add_u32_e32 v87, 0x71, v150
	v_cmp_lt_u32_e64 s[0:1], 14, v150
	v_max3_f32 v27, v27, v38, v39
	v_cndmask_b32_e32 v208, v191, v100, vcc
	v_cmp_le_u32_e32 vcc, v87, v24
	s_or_b64 s[80:81], s[44:45], s[0:1]
	v_max3_f32 v27, v27, v170, v171
	s_and_b64 vcc, vcc, s[80:81]
	v_add_u32_e32 v100, 0x72, v150
	v_cmp_lt_u32_e64 s[0:1], 13, v150
	v_max3_f32 v27, v27, v172, v173
	v_cndmask_b32_e32 v209, v191, v101, vcc
	v_cmp_le_u32_e32 vcc, v100, v24
	s_or_b64 s[82:83], s[44:45], s[0:1]
	v_max3_f32 v27, v27, v174, v175
	s_and_b64 vcc, vcc, s[82:83]
	v_add_u32_e32 v101, 0x73, v150
	v_cmp_lt_u32_e64 s[0:1], 12, v150
	v_max3_f32 v27, v27, v176, v177
	v_cndmask_b32_e32 v210, v191, v102, vcc
	v_cmp_le_u32_e32 vcc, v101, v24
	s_or_b64 s[86:87], s[44:45], s[0:1]
	v_max3_f32 v27, v27, v178, v179
	s_and_b64 vcc, vcc, s[86:87]
	v_max3_f32 v27, v27, v180, v181
	v_cndmask_b32_e32 v211, v191, v103, vcc
	v_add_u32_e32 v103, 0x81, v150
	v_max3_f32 v27, v27, v203, v204
	v_cmp_le_u32_e32 vcc, v103, v24
	v_max3_f32 v27, v27, v84, v205
	v_max3_f32 v27, v27, v206, v207
	v_cndmask_b32_e32 v53, v191, v53, vcc
	v_cmp_le_u32_e32 vcc, v164, v24
	v_max3_f32 v27, v27, v208, v209
	v_max3_f32 v27, v27, v210, v211
	v_cndmask_b32_e32 v54, v191, v54, vcc
	v_cmp_le_u32_e32 vcc, v165, v24
	v_add_u32_e32 v168, 0x92, v150
	v_max3_f32 v27, v27, v52, v53
	v_cndmask_b32_e32 v55, v191, v55, vcc
	v_cmp_le_u32_e32 vcc, v166, v24
	v_add_u32_e32 v169, 0x93, v150
	v_max3_f32 v27, v27, v54, v55
	v_cndmask_b32_e32 v28, v191, v28, vcc
	v_cmp_le_u32_e32 vcc, v167, v24
	v_or_b32_e32 v163, 0x90, v163
	v_add_u32_e32 v102, 0x80, v150
	v_cndmask_b32_e32 v29, v191, v29, vcc
	v_cmp_le_u32_e32 vcc, v168, v24
	v_max3_f32 v27, v27, v28, v29
	s_nop 0
	v_cndmask_b32_e32 v30, v191, v30, vcc
	v_cmp_le_u32_e32 vcc, v169, v24
	s_nop 1
	v_cndmask_b32_e32 v24, v191, v31, vcc
	v_max3_f32 v27, v27, v30, v24
	v_mov_b32_e32 v31, v27
	s_nop 1
	v_permlane16_swap_b32_e32 v27, v31
	s_waitcnt lgkmcnt(0)
	v_max_f32_e32 v31, v31, v31
	v_max_f32_e32 v27, v27, v31
	v_mov_b32_e32 v31, v27
	s_nop 1
	v_permlane32_swap_b32_e32 v27, v31
	s_waitcnt lgkmcnt(0)
	v_max3_f32 v27, v27, v31, v152
	v_sub_f32_e32 v25, v25, v27
	v_mul_f32_e32 v25, 0x3fb8aa3b, v25
	v_sub_f32_e32 v26, v26, v27
	v_exp_f32_e32 v25, v25
	v_mul_f32_e32 v26, 0x3fb8aa3b, v26
	v_sub_f32_e32 v32, v32, v27
	v_exp_f32_e32 v26, v26
	v_mul_f32_e32 v32, 0x3fb8aa3b, v32
	v_sub_f32_e32 v33, v33, v27
	v_exp_f32_e32 v32, v32
	v_mul_f32_e32 v33, 0x3fb8aa3b, v33
	v_sub_f32_e32 v34, v34, v27
	v_exp_f32_e32 v33, v33
	v_mul_f32_e32 v34, 0x3fb8aa3b, v34
	v_sub_f32_e32 v35, v35, v27
	v_add_f32_e32 v31, 0, v25
	v_exp_f32_e32 v34, v34
	v_mul_f32_e32 v35, 0x3fb8aa3b, v35
	v_sub_f32_e32 v36, v36, v27
	v_add_f32_e32 v31, v26, v31
	v_exp_f32_e32 v35, v35
	v_mul_f32_e32 v36, 0x3fb8aa3b, v36
	v_sub_f32_e32 v37, v37, v27
	v_add_f32_e32 v31, v32, v31
	v_exp_f32_e32 v36, v36
	v_mul_f32_e32 v37, 0x3fb8aa3b, v37
	v_sub_f32_e32 v38, v38, v27
	v_add_f32_e32 v31, v33, v31
	v_exp_f32_e32 v37, v37
	v_mul_f32_e32 v38, 0x3fb8aa3b, v38
	v_sub_f32_e32 v39, v39, v27
	v_add_f32_e32 v31, v34, v31
	v_exp_f32_e32 v38, v38
	v_mul_f32_e32 v39, 0x3fb8aa3b, v39
	v_sub_f32_e32 v170, v170, v27
	v_add_f32_e32 v31, v35, v31
	v_exp_f32_e32 v39, v39
	v_mul_f32_e32 v170, 0x3fb8aa3b, v170
	v_sub_f32_e32 v171, v171, v27
	v_add_f32_e32 v31, v36, v31
	v_exp_f32_e32 v170, v170
	v_mul_f32_e32 v171, 0x3fb8aa3b, v171
	v_sub_f32_e32 v172, v172, v27
	v_add_f32_e32 v31, v37, v31
	v_exp_f32_e32 v171, v171
	v_mul_f32_e32 v172, 0x3fb8aa3b, v172
	v_sub_f32_e32 v173, v173, v27
	v_add_f32_e32 v31, v38, v31
	v_exp_f32_e32 v172, v172
	v_mul_f32_e32 v173, 0x3fb8aa3b, v173
	v_sub_f32_e32 v174, v174, v27
	v_add_f32_e32 v31, v39, v31
	v_exp_f32_e32 v173, v173
	v_mul_f32_e32 v174, 0x3fb8aa3b, v174
	v_sub_f32_e32 v175, v175, v27
	v_add_f32_e32 v31, v170, v31
	v_exp_f32_e32 v174, v174
	v_mul_f32_e32 v175, 0x3fb8aa3b, v175
	v_sub_f32_e32 v176, v176, v27
	v_add_f32_e32 v31, v171, v31
	v_exp_f32_e32 v175, v175
	v_mul_f32_e32 v176, 0x3fb8aa3b, v176
	v_sub_f32_e32 v177, v177, v27
	v_sub_f32_e32 v84, v84, v27
	v_add_f32_e32 v31, v172, v31
	v_exp_f32_e32 v176, v176
; PH void attn_prompt_item(const Params& p, int layer, int item) {
;     ...
;       float mx = -INFINITY;
; #pragma unroll
;       for (int kt = 0; kt < 10; ++kt)
; #pragma unroll
;         for (int r = 0; r < 4; ++r) {
;           const int j = q0 + kt * 16 + quad * 4 + r;
;           const bool valid = (j >= i) && (j <= i + 128) && (nb > 0 || j >= 128);
;           const float v = valid ? s[kt][qt][r] : -INFINITY;
;           s[kt][qt][r] = v;
;           mx = fmaxf(mx, v);
;         }
;     ...
;       float sum = 0.f;
; #pragma unroll
;       for (int kt = 0; kt < 10; ++kt)
; #pragma unroll
;         for (int r = 0; r < 4; ++r) {
;           const float e = __expf(s[kt][qt][r] - mx);
;           s[kt][qt][r] = e;
;           sum += e;
;         }
;       sum += __shfl_xor(sum, 16);
;       sum += __shfl_xor(sum, 32);
;       inv[qt] = 1.f / (sum + __expf(sink - mx));
; #pragma unroll
;       for (int kk = 0; kk < 5; ++kk) pf[kk][qt] = packfrag(s[2 * kk][qt], s[2 * kk + 1][qt]);
	v_mul_f32_e32 v177, 0x3fb8aa3b, v177
	v_sub_f32_e32 v178, v178, v27
	v_mul_f32_e32 v84, 0x3fb8aa3b, v84
	v_add_f32_e32 v31, v173, v31
	v_exp_f32_e32 v177, v177
	v_mul_f32_e32 v178, 0x3fb8aa3b, v178
	v_sub_f32_e32 v179, v179, v27
	v_exp_f32_e32 v212, v84
	v_sub_f32_e32 v84, v205, v27
	v_add_f32_e32 v31, v174, v31
	v_exp_f32_e32 v178, v178
	v_mul_f32_e32 v179, 0x3fb8aa3b, v179
	v_sub_f32_e32 v180, v180, v27
	v_mul_f32_e32 v84, 0x3fb8aa3b, v84
	v_add_f32_e32 v31, v175, v31
	v_exp_f32_e32 v179, v179
	v_mul_f32_e32 v180, 0x3fb8aa3b, v180
	v_sub_f32_e32 v181, v181, v27
	v_exp_f32_e32 v205, v84
	v_sub_f32_e32 v84, v206, v27
	v_add_f32_e32 v31, v176, v31
	v_exp_f32_e32 v180, v180
	v_mul_f32_e32 v181, 0x3fb8aa3b, v181
	v_sub_f32_e32 v203, v203, v27
	v_mul_f32_e32 v84, 0x3fb8aa3b, v84
	v_add_f32_e32 v31, v177, v31
	v_exp_f32_e32 v181, v181
	v_mul_f32_e32 v203, 0x3fb8aa3b, v203
	v_sub_f32_e32 v204, v204, v27
	v_exp_f32_e32 v206, v84
	v_sub_f32_e32 v84, v207, v27
	v_add_f32_e32 v31, v178, v31
	v_exp_f32_e32 v203, v203
	v_mul_f32_e32 v204, 0x3fb8aa3b, v204
	v_mul_f32_e32 v84, 0x3fb8aa3b, v84
	v_add_f32_e32 v31, v179, v31
	v_exp_f32_e32 v204, v204
	v_exp_f32_e32 v207, v84
	v_sub_f32_e32 v84, v208, v27
	v_add_f32_e32 v31, v180, v31
	v_mul_f32_e32 v84, 0x3fb8aa3b, v84
	v_add_f32_e32 v31, v181, v31
	v_exp_f32_e32 v208, v84
	v_sub_f32_e32 v84, v209, v27
	v_add_f32_e32 v31, v203, v31
	v_mul_f32_e32 v84, 0x3fb8aa3b, v84
	v_add_f32_e32 v31, v204, v31
	v_exp_f32_e32 v209, v84
	v_sub_f32_e32 v84, v210, v27
	v_sub_f32_e32 v52, v52, v27
	v_add_f32_e32 v31, v212, v31
	v_mul_f32_e32 v84, 0x3fb8aa3b, v84
	v_mul_f32_e32 v52, 0x3fb8aa3b, v52
	v_add_f32_e32 v31, v205, v31
	v_exp_f32_e32 v210, v84
	v_sub_f32_e32 v84, v211, v27
	v_exp_f32_e32 v213, v52
	v_sub_f32_e32 v52, v53, v27
	v_add_f32_e32 v31, v206, v31
	v_mul_f32_e32 v84, 0x3fb8aa3b, v84
	v_mul_f32_e32 v52, 0x3fb8aa3b, v52
	v_add_f32_e32 v31, v207, v31
	v_exp_f32_e32 v211, v84
	v_exp_f32_e32 v214, v52
	v_sub_f32_e32 v52, v54, v27
	v_add_f32_e32 v31, v208, v31
	v_mul_f32_e32 v52, 0x3fb8aa3b, v52
	v_add_f32_e32 v31, v209, v31
	v_exp_f32_e32 v215, v52
	v_sub_f32_e32 v52, v55, v27
	v_add_f32_e32 v31, v210, v31
	v_mul_f32_e32 v52, 0x3fb8aa3b, v52
	v_sub_f32_e32 v28, v28, v27
	v_sub_f32_e32 v29, v29, v27
	v_add_f32_e32 v31, v211, v31
	v_exp_f32_e32 v216, v52
	v_mul_f32_e32 v28, 0x3fb8aa3b, v28
	v_mul_f32_e32 v29, 0x3fb8aa3b, v29
	v_add_f32_e32 v31, v213, v31
	v_exp_f32_e32 v217, v28
	v_exp_f32_e32 v218, v29
	v_sub_f32_e32 v29, v30, v27
	v_add_f32_e32 v31, v214, v31
	v_mul_f32_e32 v29, 0x3fb8aa3b, v29
	v_sub_f32_e32 v24, v24, v27
	v_add_f32_e32 v31, v215, v31
	v_exp_f32_e32 v219, v29
	v_mul_f32_e32 v24, 0x3fb8aa3b, v24
	v_add_f32_e32 v31, v216, v31
	v_exp_f32_e32 v220, v24
	v_add_f32_e32 v28, v217, v31
	v_add_f32_e32 v28, v218, v28
	v_add_f32_e32 v28, v219, v28
	v_add_f32_e32 v24, v220, v28
	v_mov_b32_e32 v28, v24
	s_nop 1
	v_permlane16_swap_b32_e32 v24, v28
	v_sub_f32_e32 v27, v152, v27
	v_mul_f32_e32 v27, 0x3fb8aa3b, v27
	v_exp_f32_e32 v27, v27
	v_cvt_pk_bf16_f32 v52, v25, v26
	s_waitcnt lgkmcnt(0)
	v_add_f32_e32 v24, v24, v28
	v_mov_b32_e32 v28, v24
	s_nop 1
	v_permlane32_swap_b32_e32 v24, v28
	v_cvt_pk_bf16_f32 v53, v32, v33
	v_cvt_pk_bf16_f32 v54, v34, v35
	v_cvt_pk_bf16_f32 v55, v36, v37
	v_cvt_pk_bf16_f32 v36, v38, v39
	s_waitcnt lgkmcnt(0)
	v_add_f32_e32 v24, v24, v28
	v_add_f32_e32 v24, v27, v24
	v_div_scale_f32 v27, s[0:1], v24, v24, 1.0
	v_rcp_f32_e32 v28, v27
	v_cmp_le_u32_e64 s[0:1], v107, v163
	v_cvt_pk_bf16_f32 v37, v170, v171
	v_cvt_pk_bf16_f32 v38, v172, v173
	v_fma_f32 v29, -v27, v28, 1.0
	v_fmac_f32_e32 v28, v29, v28
	v_div_scale_f32 v29, vcc, 1.0, v24, 1.0
	v_mul_f32_e32 v30, v29, v28
	v_fma_f32 v31, -v27, v30, v29
	v_fmac_f32_e32 v30, v31, v28
	v_fma_f32 v27, -v27, v30, v29
	v_div_fmas_f32 v27, v27, v28, v30
	v_cmp_ge_u32_e32 vcc, v150, v133
	s_and_b64 vcc, s[44:45], vcc
	v_cvt_pk_bf16_f32 v39, v174, v175
	v_cndmask_b32_e32 v40, v191, v40, vcc
	v_cmp_ge_u32_e32 vcc, v112, v133
	s_and_b64 vcc, s[44:45], vcc
	v_cvt_pk_bf16_f32 v32, v176, v177
	v_cndmask_b32_e32 v41, v191, v41, vcc
	v_cmp_ge_u32_e32 vcc, v113, v133
	s_and_b64 vcc, s[44:45], vcc
	v_max3_f32 v112, v40, s96, v41
	v_cndmask_b32_e32 v42, v191, v42, vcc
	v_cmp_ge_u32_e32 vcc, v114, v133
	s_and_b64 vcc, s[44:45], vcc
	v_cvt_pk_bf16_f32 v33, v178, v179
	v_cndmask_b32_e32 v43, v191, v43, vcc
	v_cmp_ge_u32_e32 vcc, v108, v133
	s_and_b64 vcc, s[44:45], vcc
	v_max3_f32 v112, v112, v42, v43
	v_cndmask_b32_e32 v45, v191, v45, vcc
	v_cmp_ge_u32_e32 vcc, v109, v133
	s_and_b64 vcc, s[44:45], vcc
	v_max3_f32 v108, v112, v44, v45
	v_cndmask_b32_e32 v46, v191, v46, vcc
	v_cmp_ge_u32_e32 vcc, v110, v133
	s_and_b64 vcc, s[44:45], vcc
	v_cvt_pk_bf16_f32 v34, v180, v181
	v_cndmask_b32_e32 v47, v191, v47, vcc
	v_cmp_ge_u32_e32 vcc, v111, v133
	s_and_b64 vcc, vcc, s[8:9]
	v_max3_f32 v108, v108, v46, v47
	v_cndmask_b32_e32 v56, v191, v56, vcc
	v_cmp_ge_u32_e32 vcc, v104, v133
	s_and_b64 vcc, vcc, s[46:47]
	v_cvt_pk_bf16_f32 v35, v203, v204
	v_cndmask_b32_e32 v57, v191, v57, vcc
	v_cmp_ge_u32_e32 vcc, v105, v133
	s_and_b64 vcc, vcc, s[50:51]
	v_max3_f32 v104, v108, v56, v57
	v_cndmask_b32_e32 v58, v191, v58, vcc
	v_cmp_ge_u32_e32 vcc, v106, v133
	s_and_b64 vcc, vcc, s[52:53]
	v_cvt_pk_bf16_f32 v28, v212, v205
	v_cndmask_b32_e32 v59, v191, v59, vcc
	v_cmp_ge_u32_e32 vcc, v107, v133
	s_and_b64 s[0:1], vcc, s[0:1]
	s_and_b64 vcc, s[0:1], s[8:9]
	v_cndmask_b32_e32 v48, v191, v48, vcc
	v_cmp_ge_u32_e32 vcc, v96, v133
	v_cmp_le_u32_e64 s[0:1], v96, v163
	s_and_b64 s[0:1], vcc, s[0:1]
	s_and_b64 vcc, s[0:1], s[54:55]
	v_cndmask_b32_e32 v49, v191, v49, vcc
; PH void attn_prompt_item(const Params& p, int layer, int item) {
;     ...
;       float mx = -INFINITY;
; #pragma unroll
;       for (int kt = 0; kt < 10; ++kt)
; #pragma unroll
;         for (int r = 0; r < 4; ++r) {
;           const int j = q0 + kt * 16 + quad * 4 + r;
;           const bool valid = (j >= i) && (j <= i + 128) && (nb > 0 || j >= 128);
;           const float v = valid ? s[kt][qt][r] : -INFINITY;
;           s[kt][qt][r] = v;
;           mx = fmaxf(mx, v);
;         }
;       mx = fmaxf(mx, __shfl_xor(mx, 16));
;       mx = fmaxf(mx, __shfl_xor(mx, 32));
	v_cmp_ge_u32_e32 vcc, v97, v133
	v_cmp_le_u32_e64 s[0:1], v97, v163
	s_and_b64 s[0:1], vcc, s[0:1]
	s_and_b64 vcc, s[0:1], s[56:57]
	v_cndmask_b32_e32 v50, v191, v50, vcc
	v_cmp_ge_u32_e32 vcc, v98, v133
	v_cmp_le_u32_e64 s[0:1], v98, v163
	s_and_b64 s[0:1], vcc, s[0:1]
	s_and_b64 vcc, s[0:1], s[58:59]
	v_cndmask_b32_e32 v51, v191, v51, vcc
	v_cmp_ge_u32_e32 vcc, v99, v133
	v_cmp_le_u32_e64 s[0:1], v99, v163
	s_and_b64 s[0:1], vcc, s[0:1]
	s_and_b64 vcc, s[0:1], s[48:49]
	v_cndmask_b32_e32 v60, v191, v60, vcc
	v_cmp_ge_u32_e32 vcc, v88, v133
	v_cmp_le_u32_e64 s[0:1], v88, v163
	s_and_b64 s[0:1], vcc, s[0:1]
	s_and_b64 vcc, s[0:1], s[62:63]
	v_cndmask_b32_e32 v61, v191, v61, vcc
	v_cmp_ge_u32_e32 vcc, v89, v133
	v_cmp_le_u32_e64 s[0:1], v89, v163
	s_and_b64 s[0:1], vcc, s[0:1]
	s_and_b64 vcc, s[0:1], s[64:65]
	v_cndmask_b32_e32 v62, v191, v62, vcc
	v_cmp_ge_u32_e32 vcc, v90, v133
	v_cmp_le_u32_e64 s[0:1], v90, v163
	s_and_b64 s[0:1], vcc, s[0:1]
	s_and_b64 vcc, s[0:1], s[66:67]
	v_cndmask_b32_e32 v63, v191, v63, vcc
	v_cmp_ge_u32_e32 vcc, v91, v133
	v_cmp_le_u32_e64 s[0:1], v91, v163
	s_and_b64 s[0:1], vcc, s[0:1]
	s_and_b64 vcc, s[0:1], s[48:49]
	v_cndmask_b32_e32 v64, v191, v64, vcc
	v_cmp_ge_u32_e32 vcc, v92, v133
	v_cmp_le_u32_e64 s[0:1], v92, v163
	s_and_b64 s[0:1], vcc, s[0:1]
	s_and_b64 vcc, s[0:1], s[68:69]
	v_cndmask_b32_e32 v65, v191, v65, vcc
	v_cmp_ge_u32_e32 vcc, v93, v133
	v_cmp_le_u32_e64 s[0:1], v93, v163
	s_and_b64 s[0:1], vcc, s[0:1]
	s_and_b64 vcc, s[0:1], s[70:71]
	v_cndmask_b32_e32 v66, v191, v66, vcc
	v_cmp_ge_u32_e32 vcc, v94, v133
	v_cmp_le_u32_e64 s[0:1], v94, v163
	s_and_b64 s[0:1], vcc, s[0:1]
	s_and_b64 vcc, s[0:1], s[72:73]
	v_cndmask_b32_e32 v67, v191, v67, vcc
	v_cmp_ge_u32_e32 vcc, v95, v133
	v_cmp_le_u32_e64 s[0:1], v95, v163
	s_and_b64 s[0:1], vcc, s[0:1]
	s_and_b64 vcc, s[60:61], s[0:1]
	v_cndmask_b32_e32 v68, v191, v68, vcc
	v_cmp_ge_u32_e32 vcc, v115, v133
	v_cmp_le_u32_e64 s[0:1], v115, v163
	s_and_b64 s[0:1], vcc, s[0:1]
	s_and_b64 vcc, s[0:1], s[74:75]
	v_cndmask_b32_e32 v69, v191, v69, vcc
	v_cmp_ge_u32_e32 vcc, v85, v133
	v_cmp_le_u32_e64 s[0:1], v85, v163
	s_and_b64 s[0:1], vcc, s[0:1]
	s_and_b64 vcc, s[0:1], s[76:77]
	v_cndmask_b32_e32 v70, v191, v70, vcc
	v_cmp_ge_u32_e32 vcc, v86, v133
	v_cmp_le_u32_e64 s[0:1], v86, v163
	s_and_b64 s[0:1], vcc, s[0:1]
	s_and_b64 vcc, s[0:1], s[78:79]
	v_cndmask_b32_e32 v71, v191, v71, vcc
	v_cmp_ge_u32_e32 vcc, v151, v133
	v_cmp_le_u32_e64 s[0:1], v151, v163
	s_and_b64 s[0:1], vcc, s[0:1]
	s_and_b64 vcc, s[60:61], s[0:1]
	v_cndmask_b32_e32 v72, v191, v72, vcc
	v_cmp_ge_u32_e32 vcc, v87, v133
	v_cmp_le_u32_e64 s[0:1], v87, v163
	s_and_b64 s[0:1], vcc, s[0:1]
	s_and_b64 vcc, s[0:1], s[80:81]
	v_cndmask_b32_e32 v73, v191, v73, vcc
	v_cmp_ge_u32_e32 vcc, v100, v133
	v_cmp_le_u32_e64 s[0:1], v100, v163
	v_max3_f32 v104, v104, v58, v59
	s_and_b64 s[0:1], vcc, s[0:1]
	v_max3_f32 v96, v104, v48, v49
	s_and_b64 vcc, s[0:1], s[82:83]
	v_max3_f32 v96, v96, v50, v51
	v_cndmask_b32_e32 v74, v191, v74, vcc
	v_cmp_ge_u32_e32 vcc, v101, v133
	v_cmp_le_u32_e64 s[0:1], v101, v163
	v_max3_f32 v88, v96, v60, v61
	s_and_b64 s[0:1], vcc, s[0:1]
	v_max3_f32 v88, v88, v62, v63
	s_and_b64 vcc, s[0:1], s[86:87]
	v_max3_f32 v88, v88, v64, v65
	v_cndmask_b32_e32 v75, v191, v75, vcc
	v_cmp_le_u32_e32 vcc, v102, v163
	v_max3_f32 v88, v88, v66, v67
	v_max3_f32 v88, v88, v68, v69
	v_cndmask_b32_e32 v76, v191, v76, vcc
	v_cmp_le_u32_e32 vcc, v103, v163
	v_max3_f32 v85, v88, v70, v71
	v_max3_f32 v85, v85, v72, v73
	v_cndmask_b32_e32 v77, v191, v77, vcc
	v_cmp_le_u32_e32 vcc, v164, v163
	v_max3_f32 v85, v85, v74, v75
	v_max3_f32 v85, v85, v76, v77
	v_cndmask_b32_e32 v78, v191, v78, vcc
	v_cmp_le_u32_e32 vcc, v165, v163
	v_cvt_pk_bf16_f32 v29, v206, v207
	v_cvt_pk_bf16_f32 v30, v208, v209
	v_cndmask_b32_e32 v79, v191, v79, vcc
	v_cmp_le_u32_e32 vcc, v166, v163
	v_max3_f32 v85, v85, v78, v79
	v_cvt_pk_bf16_f32 v31, v210, v211
	v_cndmask_b32_e32 v80, v191, v80, vcc
	v_cmp_le_u32_e32 vcc, v167, v163
	v_div_fixup_f32 v84, v27, v24, 1.0
	v_cvt_pk_bf16_f32 v24, v213, v214
	v_cndmask_b32_e32 v81, v191, v81, vcc
	v_cmp_le_u32_e32 vcc, v168, v163
	v_max3_f32 v85, v85, v80, v81
	v_cvt_pk_bf16_f32 v25, v215, v216
	v_cndmask_b32_e32 v82, v191, v82, vcc
	v_cmp_le_u32_e32 vcc, v169, v163
	v_cvt_pk_bf16_f32 v26, v217, v218
	v_cvt_pk_bf16_f32 v27, v219, v220
	v_cndmask_b32_e32 v83, v191, v83, vcc
	v_max3_f32 v85, v85, v82, v83
	v_mov_b32_e32 v86, v85
	s_nop 1
	v_permlane16_swap_b32_e32 v85, v86
	s_cmp_eq_u32 s2, 4
	s_waitcnt lgkmcnt(0)
	v_max_f32_e32 v86, v86, v86
	v_max_f32_e32 v85, v85, v86
	v_mov_b32_e32 v86, v85
	s_nop 1
	v_permlane32_swap_b32_e32 v85, v86
	s_waitcnt lgkmcnt(0)
; PH void attn_prompt_item(const Params& p, int layer, int item) {
;     ...
;       mx = fmaxf(mx, sink);
;       float sum = 0.f;
; #pragma unroll
;       for (int kt = 0; kt < 10; ++kt)
; #pragma unroll
;         for (int r = 0; r < 4; ++r) {
;           const float e = __expf(s[kt][qt][r] - mx);
;           s[kt][qt][r] = e;
;           sum += e;
;         }
;       sum += __shfl_xor(sum, 16);
;       sum += __shfl_xor(sum, 32);
;       inv[qt] = 1.f / (sum + __expf(sink - mx));
; #pragma unroll
;       for (int kk = 0; kk < 5; ++kk) pf[kk][qt] = packfrag(s[2 * kk][qt], s[2 * kk + 1][qt]);
;     }
;     f32x4 o[4][2];
; #pragma unroll
;     for (int dt = 0; dt < 4; ++dt) { o[dt][0] = (f32x4){0.f, 0.f, 0.f, 0.f}; o[dt][1] = (f32x4){0.f, 0.f, 0.f, 0.f}; }
; #pragma unroll
;     for (int kk = 0; kk < 5; ++kk)
; #pragma unroll
;       for (int dt = 0; dt < 4; ++dt) {
;         const bf16x8 vf = ldfrag_perm(Vt, 264, dt * 16, q0 + kk * 32, lane);
	v_max3_f32 v85, v85, v86, v152
	v_sub_f32_e32 v40, v40, v85
	v_mul_f32_e32 v40, 0x3fb8aa3b, v40
	v_sub_f32_e32 v41, v41, v85
	v_exp_f32_e32 v40, v40
	v_mul_f32_e32 v41, 0x3fb8aa3b, v41
	v_sub_f32_e32 v42, v42, v85
	v_exp_f32_e32 v41, v41
	v_mul_f32_e32 v42, 0x3fb8aa3b, v42
	v_sub_f32_e32 v43, v43, v85
	v_exp_f32_e32 v42, v42
	v_mul_f32_e32 v43, 0x3fb8aa3b, v43
	v_sub_f32_e32 v44, v44, v85
	v_exp_f32_e32 v43, v43
	v_mul_f32_e32 v44, 0x3fb8aa3b, v44
	v_sub_f32_e32 v45, v45, v85
	v_add_f32_e32 v86, 0, v40
	v_exp_f32_e32 v44, v44
	v_mul_f32_e32 v45, 0x3fb8aa3b, v45
	v_sub_f32_e32 v46, v46, v85
	v_add_f32_e32 v86, v41, v86
	v_exp_f32_e32 v45, v45
	v_mul_f32_e32 v46, 0x3fb8aa3b, v46
	v_sub_f32_e32 v47, v47, v85
	v_add_f32_e32 v86, v42, v86
	v_exp_f32_e32 v46, v46
	v_mul_f32_e32 v47, 0x3fb8aa3b, v47
	v_sub_f32_e32 v56, v56, v85
	v_add_f32_e32 v86, v43, v86
	v_exp_f32_e32 v47, v47
	v_mul_f32_e32 v56, 0x3fb8aa3b, v56
	v_sub_f32_e32 v57, v57, v85
	v_add_f32_e32 v86, v44, v86
	v_exp_f32_e32 v56, v56
	v_mul_f32_e32 v57, 0x3fb8aa3b, v57
	v_sub_f32_e32 v58, v58, v85
	v_add_f32_e32 v86, v45, v86
	v_exp_f32_e32 v57, v57
	v_mul_f32_e32 v58, 0x3fb8aa3b, v58
	v_sub_f32_e32 v59, v59, v85
	v_add_f32_e32 v86, v46, v86
	v_exp_f32_e32 v58, v58
	v_mul_f32_e32 v59, 0x3fb8aa3b, v59
	v_sub_f32_e32 v48, v48, v85
	v_add_f32_e32 v86, v47, v86
	v_exp_f32_e32 v59, v59
	v_mul_f32_e32 v48, 0x3fb8aa3b, v48
	v_sub_f32_e32 v49, v49, v85
	v_add_f32_e32 v86, v56, v86
	v_exp_f32_e32 v48, v48
	v_mul_f32_e32 v49, 0x3fb8aa3b, v49
	v_sub_f32_e32 v50, v50, v85
	v_add_f32_e32 v86, v57, v86
	v_exp_f32_e32 v49, v49
	v_mul_f32_e32 v50, 0x3fb8aa3b, v50
	v_sub_f32_e32 v51, v51, v85
	v_add_f32_e32 v86, v58, v86
	v_exp_f32_e32 v50, v50
	v_mul_f32_e32 v51, 0x3fb8aa3b, v51
	v_sub_f32_e32 v60, v60, v85
	v_add_f32_e32 v86, v59, v86
	v_exp_f32_e32 v51, v51
	v_mul_f32_e32 v60, 0x3fb8aa3b, v60
	v_add_f32_e32 v86, v48, v86
	v_exp_f32_e32 v87, v60
	v_add_f32_e32 v86, v49, v86
	v_add_f32_e32 v86, v50, v86
	v_sub_f32_e32 v61, v61, v85
	v_add_f32_e32 v86, v51, v86
	v_mul_f32_e32 v61, 0x3fb8aa3b, v61
	v_add_f32_e32 v60, v87, v86
	v_exp_f32_e32 v86, v61
	v_sub_f32_e32 v61, v62, v85
	v_mul_f32_e32 v61, 0x3fb8aa3b, v61
	v_exp_f32_e32 v88, v61
	v_sub_f32_e32 v61, v63, v85
	v_mul_f32_e32 v61, 0x3fb8aa3b, v61
	v_exp_f32_e32 v89, v61
	v_sub_f32_e32 v61, v64, v85
	v_mul_f32_e32 v61, 0x3fb8aa3b, v61
	v_exp_f32_e32 v90, v61
	v_sub_f32_e32 v61, v65, v85
	v_mul_f32_e32 v61, 0x3fb8aa3b, v61
	v_exp_f32_e32 v65, v61
	v_sub_f32_e32 v61, v66, v85
	v_mul_f32_e32 v61, 0x3fb8aa3b, v61
	v_exp_f32_e32 v66, v61
	v_sub_f32_e32 v61, v67, v85
	v_mul_f32_e32 v61, 0x3fb8aa3b, v61
	v_exp_f32_e32 v67, v61
	v_sub_f32_e32 v61, v68, v85
	v_mul_f32_e32 v61, 0x3fb8aa3b, v61
	v_exp_f32_e32 v68, v61
	v_sub_f32_e32 v61, v69, v85
	v_mul_f32_e32 v61, 0x3fb8aa3b, v61
	v_exp_f32_e32 v69, v61
	v_sub_f32_e32 v61, v70, v85
	v_mul_f32_e32 v61, 0x3fb8aa3b, v61
	v_exp_f32_e32 v70, v61
	v_sub_f32_e32 v61, v71, v85
	v_mul_f32_e32 v61, 0x3fb8aa3b, v61
	v_exp_f32_e32 v71, v61
	v_sub_f32_e32 v61, v72, v85
	v_mul_f32_e32 v61, 0x3fb8aa3b, v61
	v_exp_f32_e32 v72, v61
	v_sub_f32_e32 v61, v73, v85
	v_mul_f32_e32 v61, 0x3fb8aa3b, v61
	v_exp_f32_e32 v73, v61
	v_sub_f32_e32 v61, v74, v85
	v_mul_f32_e32 v61, 0x3fb8aa3b, v61
	v_add_f32_e32 v60, v86, v60
	v_exp_f32_e32 v74, v61
	v_sub_f32_e32 v61, v75, v85
	v_add_f32_e32 v60, v88, v60
	v_mul_f32_e32 v61, 0x3fb8aa3b, v61
	v_add_f32_e32 v60, v89, v60
	v_exp_f32_e32 v75, v61
	v_sub_f32_e32 v61, v76, v85
	v_add_f32_e32 v60, v90, v60
	v_mul_f32_e32 v61, 0x3fb8aa3b, v61
	v_add_f32_e32 v60, v65, v60
	v_exp_f32_e32 v76, v61
	v_sub_f32_e32 v61, v77, v85
	v_add_f32_e32 v60, v66, v60
	v_mul_f32_e32 v61, 0x3fb8aa3b, v61
	v_add_f32_e32 v60, v67, v60
	v_exp_f32_e32 v77, v61
	v_sub_f32_e32 v61, v78, v85
	v_add_f32_e32 v60, v68, v60
	v_mul_f32_e32 v61, 0x3fb8aa3b, v61
	v_add_f32_e32 v60, v69, v60
	v_exp_f32_e32 v78, v61
	v_sub_f32_e32 v61, v79, v85
	v_add_f32_e32 v60, v70, v60
	v_mul_f32_e32 v61, 0x3fb8aa3b, v61
	v_add_f32_e32 v60, v71, v60
	v_exp_f32_e32 v79, v61
	v_sub_f32_e32 v61, v80, v85
	v_add_f32_e32 v60, v72, v60
	v_mul_f32_e32 v61, 0x3fb8aa3b, v61
	v_add_f32_e32 v60, v73, v60
	v_exp_f32_e32 v80, v61
	v_sub_f32_e32 v61, v81, v85
	v_add_f32_e32 v60, v74, v60
	v_mul_f32_e32 v61, 0x3fb8aa3b, v61
	v_add_f32_e32 v60, v75, v60
	v_exp_f32_e32 v81, v61
	v_sub_f32_e32 v61, v82, v85
	v_add_f32_e32 v60, v76, v60
	v_mul_f32_e32 v61, 0x3fb8aa3b, v61
	v_add_f32_e32 v60, v77, v60
	v_exp_f32_e32 v82, v61
	v_sub_f32_e32 v61, v83, v85
	v_add_f32_e32 v60, v78, v60
	v_mul_f32_e32 v61, 0x3fb8aa3b, v61
	v_add_f32_e32 v60, v79, v60
	v_exp_f32_e32 v83, v61
	v_add_f32_e32 v60, v80, v60
	v_add_f32_e32 v60, v81, v60
	v_add_f32_e32 v60, v82, v60
	v_add_f32_e32 v60, v83, v60
	v_mov_b32_e32 v61, v60
	s_nop 1
	v_permlane16_swap_b32_e32 v60, v61
	v_cvt_pk_bf16_f32 v56, v56, v57
	v_cvt_pk_bf16_f32 v57, v58, v59
	v_cvt_pk_bf16_f32 v59, v50, v51
	v_cvt_pk_bf16_f32 v50, v90, v65
	s_waitcnt lgkmcnt(0)
	v_add_f32_e32 v60, v60, v61
	v_mov_b32_e32 v61, v60
	s_nop 1
	v_permlane32_swap_b32_e32 v60, v61
	v_lshl_add_u32 v65, s15, 6, v159
	v_cvt_pk_bf16_f32 v51, v66, v67
	v_add_u32_e32 v66, 0xb000, v65
	v_add_u32_e32 v67, 0xd000, v65
	s_waitcnt lgkmcnt(0)
	v_add_f32_e32 v60, v60, v61
	v_sub_f32_e32 v61, v152, v85
	v_mul_f32_e32 v61, 0x3fb8aa3b, v61
	v_exp_f32_e32 v61, v61
	ds_read2_b64 v[90:93], v67 offset0:64 offset1:68
	v_cvt_pk_bf16_f32 v58, v48, v49
	v_cvt_pk_bf16_f32 v48, v87, v86
	v_add_f32_e32 v60, v61, v60
	v_div_scale_f32 v61, s[0:1], v60, v60, 1.0
	v_rcp_f32_e32 v62, v61
	v_cvt_pk_bf16_f32 v49, v88, v89
	s_waitcnt lgkmcnt(0)
; DI unsigned pack2(float a, float b) { fl2_t v = {a, b}; return __builtin_bit_cast(unsigned, __builtin_convertvector(v, bf2_t)); }
; DI float bflo(unsigned u) { return __uint_as_float(u << 16); }
; DI float bfhi(unsigned u) { return __uint_as_float(u & 0xffff0000u); }
; DI f32x4 mfma16(bf16x8 a, bf16x8 b, f32x4 c) { return __builtin_amdgcn_mfma_f32_16x16x32_bf16(a, b, c, 0, 0, 0); }
; DI float silu_f(float x) { return x * __builtin_amdgcn_rcpf(1.f + __expf(-x)); }
; PH void attn_prompt_item(const Params& p, int layer, int item) {
;     ...
;     f32x4 o[4][2];
; #pragma unroll
;     for (int dt = 0; dt < 4; ++dt) { o[dt][0] = (f32x4){0.f, 0.f, 0.f, 0.f}; o[dt][1] = (f32x4){0.f, 0.f, 0.f, 0.f}; }
; #pragma unroll
;     for (int kk = 0; kk < 5; ++kk)
; #pragma unroll
;       for (int dt = 0; dt < 4; ++dt) {
;         const bf16x8 vf = ldfrag_perm(Vt, 264, dt * 16, q0 + kk * 32, lane);
;         o[dt][0] = mfma16(vf, pf[kk][0], o[dt][0]);
;         o[dt][1] = mfma16(vf, pf[kk][1], o[dt][1]);
;       }
; #pragma unroll
;     for (int qt = 0; qt < 2; ++qt) {
;       const int qi = q0 + qt * 16 + l15;
;       const size_t row = (size_t)(b * 2048 + nb * 128 + qi);
; #pragma unroll
;       for (int dt = 0; dt < 4; ++dt) {
;         const int col = h * 64 + dt * 16 + quad * 4;
;         const uint2 gv = gpre[qt][dt];
;         const float g0 = bflo(gv.x), g1 = bfhi(gv.x), g2 = bflo(gv.y), g3 = bfhi(gv.y);
;         uint2 ov;
;         ov.x = pack2(o[dt][qt][0] * inv[qt] * silu_f(g0), o[dt][qt][1] * inv[qt] * silu_f(g1));
;         ov.y = pack2(o[dt][qt][2] * inv[qt] * silu_f(g2), o[dt][qt][3] * inv[qt] * silu_f(g3));
	v_mfma_f32_16x16x32_bf16 v[94:97], v[90:93], v[52:55], 0
	v_fma_f32 v63, -v61, v62, 1.0
	v_fmac_f32_e32 v62, v63, v62
	v_div_scale_f32 v63, vcc, 1.0, v60, 1.0
	v_mul_f32_e32 v64, v63, v62
	v_fma_f32 v85, -v61, v64, v63
	v_fmac_f32_e32 v64, v85, v62
	v_fma_f32 v61, -v61, v64, v63
	v_div_fmas_f32 v61, v61, v62, v64
	v_cvt_pk_bf16_f32 v62, v44, v45
	v_cvt_pk_bf16_f32 v44, v68, v69
	v_add_u32_e32 v68, 0x9000, v65
	v_add_u32_e32 v65, 0xf000, v65
	v_div_fixup_f32 v64, v61, v60, 1.0
	v_cvt_pk_bf16_f32 v60, v40, v41
	v_cvt_pk_bf16_f32 v61, v42, v43
	v_cvt_pk_bf16_f32 v63, v46, v47
	v_cvt_pk_bf16_f32 v45, v70, v71
	v_cvt_pk_bf16_f32 v46, v72, v73
	v_cvt_pk_bf16_f32 v41, v78, v79
	v_cvt_pk_bf16_f32 v42, v80, v81
	ds_read2_b64 v[70:73], v68 offset1:4
	ds_read2_b64 v[78:81], v66 offset0:32 offset1:36
	ds_read2_b64 v[98:101], v65 offset0:96 offset1:100
	v_lshl_add_u32 v69, s2, 6, v159
	v_cvt_pk_bf16_f32 v43, v82, v83
	v_add_u32_e32 v82, 0x9000, v69
	v_cvt_pk_bf16_f32 v47, v74, v75
	v_cvt_pk_bf16_f32 v40, v76, v77
	s_waitcnt lgkmcnt(2)
	v_mfma_f32_16x16x32_bf16 v[74:77], v[70:73], v[52:55], 0
	s_mov_b64 s[0:1], 0x10000
	s_mov_b32 s15, s2
	v_mfma_f32_16x16x32_bf16 v[70:73], v[70:73], v[60:63], 0
	s_waitcnt lgkmcnt(1)
	v_mfma_f32_16x16x32_bf16 v[86:89], v[78:81], v[52:55], 0
	v_mfma_f32_16x16x32_bf16 v[78:81], v[78:81], v[60:63], 0
	v_mfma_f32_16x16x32_bf16 v[90:93], v[90:93], v[60:63], 0
	s_waitcnt lgkmcnt(0)
	v_mfma_f32_16x16x32_bf16 v[52:55], v[98:101], v[52:55], 0
	v_mfma_f32_16x16x32_bf16 v[60:63], v[98:101], v[60:63], 0
	ds_read2_b64 v[98:101], v82 offset1:4
	v_add_u32_e32 v82, 0xb000, v69
	s_waitcnt lgkmcnt(0)
	v_mfma_f32_16x16x32_bf16 v[74:77], v[98:101], v[36:39], v[74:77]
	v_mfma_f32_16x16x32_bf16 v[70:73], v[98:101], v[56:59], v[70:73]
	ds_read2_b64 v[98:101], v82 offset0:32 offset1:36
	v_add_u32_e32 v82, 0xd000, v69
	v_add_u32_e32 v69, 0xf000, v69
	s_waitcnt lgkmcnt(0)
	v_mfma_f32_16x16x32_bf16 v[86:89], v[98:101], v[36:39], v[86:89]
	v_mfma_f32_16x16x32_bf16 v[78:81], v[98:101], v[56:59], v[78:81]
	ds_read2_b64 v[98:101], v82 offset0:64 offset1:68
	s_waitcnt lgkmcnt(0)
	v_mfma_f32_16x16x32_bf16 v[94:97], v[98:101], v[36:39], v[94:97]
	v_mfma_f32_16x16x32_bf16 v[90:93], v[98:101], v[56:59], v[90:93]
	ds_read2_b64 v[98:101], v69 offset0:96 offset1:100
	s_waitcnt lgkmcnt(0)
	v_mfma_f32_16x16x32_bf16 v[36:39], v[98:101], v[36:39], v[52:55]
	v_mfma_f32_16x16x32_bf16 v[52:55], v[98:101], v[56:59], v[60:63]
	ds_read2_b64 v[56:59], v68 offset0:16 offset1:20
	s_waitcnt lgkmcnt(0)
	v_mfma_f32_16x16x32_bf16 v[60:63], v[56:59], v[32:35], v[74:77]
	v_mfma_f32_16x16x32_bf16 v[56:59], v[56:59], v[48:51], v[70:73]
	s_nop 2
	ds_read2_b64 v[70:73], v66 offset0:48 offset1:52
	s_waitcnt lgkmcnt(0)
	v_mfma_f32_16x16x32_bf16 v[74:77], v[70:73], v[32:35], v[86:89]
	v_mfma_f32_16x16x32_bf16 v[70:73], v[70:73], v[48:51], v[78:81]
	s_nop 2
	ds_read2_b64 v[78:81], v67 offset0:80 offset1:84
	s_waitcnt lgkmcnt(0)
	v_mfma_f32_16x16x32_bf16 v[86:89], v[78:81], v[32:35], v[94:97]
	v_mfma_f32_16x16x32_bf16 v[78:81], v[78:81], v[48:51], v[90:93]
	s_nop 2
	ds_read2_b64 v[90:93], v65 offset0:112 offset1:116
	s_waitcnt lgkmcnt(0)
	v_mfma_f32_16x16x32_bf16 v[32:35], v[90:93], v[32:35], v[36:39]
	v_mfma_f32_16x16x32_bf16 v[36:39], v[90:93], v[48:51], v[52:55]
	ds_read2_b64 v[48:51], v68 offset0:24 offset1:28
	s_waitcnt lgkmcnt(0)
	v_mfma_f32_16x16x32_bf16 v[52:55], v[48:51], v[28:31], v[60:63]
	v_mfma_f32_16x16x32_bf16 v[48:51], v[48:51], v[44:47], v[56:59]
	s_nop 2
	ds_read2_b64 v[56:59], v66 offset0:56 offset1:60
	s_waitcnt lgkmcnt(0)
	v_mfma_f32_16x16x32_bf16 v[60:63], v[56:59], v[28:31], v[74:77]
	v_mfma_f32_16x16x32_bf16 v[56:59], v[56:59], v[44:47], v[70:73]
	s_nop 2
	ds_read2_b64 v[70:73], v67 offset0:88 offset1:92
	s_waitcnt lgkmcnt(0)
	v_mfma_f32_16x16x32_bf16 v[74:77], v[70:73], v[28:31], v[86:89]
	v_mfma_f32_16x16x32_bf16 v[70:73], v[70:73], v[44:47], v[78:81]
	s_nop 2
	ds_read2_b64 v[78:81], v65 offset0:120 offset1:124
	s_waitcnt lgkmcnt(0)
	v_mfma_f32_16x16x32_bf16 v[86:89], v[78:81], v[28:31], v[32:35]
	ds_read2_b64 v[28:31], v68 offset0:32 offset1:36
	v_mfma_f32_16x16x32_bf16 v[78:81], v[78:81], v[44:47], v[36:39]
	s_waitcnt lgkmcnt(0)
	v_mfma_f32_16x16x32_bf16 v[90:93], v[28:31], v[24:27], v[52:55]
	v_mfma_f32_16x16x32_bf16 v[36:39], v[28:31], v[40:43], v[48:51]
	ds_read2_b64 v[28:31], v66 offset0:64 offset1:68
	s_waitcnt lgkmcnt(0)
	v_mfma_f32_16x16x32_bf16 v[52:55], v[28:31], v[24:27], v[60:63]
	s_nop 3
	v_mul_f32_e64 v60, v84, v90
	v_mul_f32_e64 v61, v84, v91
	v_pk_mul_f32 v[36:37], v[64:65], v[36:37] op_sel_hi:[0,1]
	v_pk_mul_f32 v[38:39], v[64:65], v[38:39] op_sel_hi:[0,1]
	v_mfma_f32_16x16x32_bf16 v[32:35], v[28:31], v[40:43], v[56:59]
	ds_read2_b64 v[28:31], v67 offset0:96 offset1:100
	v_pk_mul_f32 v[52:53], v[84:85], v[52:53] op_sel_hi:[0,1]
	v_pk_mul_f32 v[54:55], v[84:85], v[54:55] op_sel_hi:[0,1]
	ds_read2_b64 v[56:59], v65 offset0:128 offset1:132
	s_waitcnt lgkmcnt(1)
	v_mfma_f32_16x16x32_bf16 v[48:51], v[28:31], v[24:27], v[74:77]
	s_nop 1
	v_mul_f32_e64 v32, v64, v32
	v_mul_f32_e64 v33, v64, v33
	v_pk_mul_f32 v[34:35], v[64:65], v[34:35] op_sel_hi:[0,1]
	s_nop 2
	v_pk_mul_f32 v[48:49], v[84:85], v[48:49] op_sel_hi:[0,1]
	v_mfma_f32_16x16x32_bf16 v[28:31], v[28:31], v[40:43], v[70:73]
	v_mul_f32_e64 v50, v84, v50
	v_mul_f32_e64 v51, v84, v51
	s_waitcnt lgkmcnt(0)
	v_mfma_f32_16x16x32_bf16 v[44:47], v[56:59], v[24:27], v[86:89]
	v_mfma_f32_16x16x32_bf16 v[24:27], v[56:59], v[40:43], v[78:81]
	s_waitcnt vmcnt(7)
; DI unsigned pack2(float a, float b) { fl2_t v = {a, b}; return __builtin_bit_cast(unsigned, __builtin_convertvector(v, bf2_t)); }
; DI float bflo(unsigned u) { return __uint_as_float(u << 16); }
; DI float bfhi(unsigned u) { return __uint_as_float(u & 0xffff0000u); }
; DI float silu_f(float x) { return x * __builtin_amdgcn_rcpf(1.f + __expf(-x)); }
; PH void attn_prompt_item(const Params& p, int layer, int item) {
;     ...
; #pragma unroll
;     for (int qt = 0; qt < 2; ++qt) {
;       const int qi = q0 + qt * 16 + l15;
;       const size_t row = (size_t)(b * 2048 + nb * 128 + qi);
; #pragma unroll
;       for (int dt = 0; dt < 4; ++dt) {
;         const int col = h * 64 + dt * 16 + quad * 4;
;         const uint2 gv = gpre[qt][dt];
;         const float g0 = bflo(gv.x), g1 = bfhi(gv.x), g2 = bflo(gv.y), g3 = bfhi(gv.y);
;         uint2 ov;
;         ov.x = pack2(o[dt][qt][0] * inv[qt] * silu_f(g0), o[dt][qt][1] * inv[qt] * silu_f(g1));
;         ov.y = pack2(o[dt][qt][2] * inv[qt] * silu_f(g2), o[dt][qt][3] * inv[qt] * silu_f(g3));
;         *(uint2*)(MIX + row * 2048 + col) = ov;
;       }
;     }
	v_lshlrev_b32_e32 v42, 16, v148
	v_and_b32_e32 v43, 0xffff0000, v148
	v_mul_f32_e32 v58, 0xbfb8aa3b, v42
	v_mul_f32_e32 v59, 0xbfb8aa3b, v43
	v_exp_f32_e32 v58, v58
	v_exp_f32_e32 v59, v59
	v_lshlrev_b32_e32 v56, 16, v149
	v_and_b32_e32 v57, 0xffff0000, v149
	v_add_f32_e32 v58, 1.0, v58
	v_add_f32_e32 v59, 1.0, v59
	v_rcp_f32_e32 v58, v58
	v_rcp_f32_e32 v59, v59
	v_add_lshl_u32 v40, v158, s7, 11
	v_mov_b32_e32 v41, v161
	v_pk_mul_f32 v[44:45], v[84:85], v[44:45] op_sel_hi:[0,1]
	v_pk_mul_f32 v[42:43], v[58:59], v[42:43]
	v_pk_mul_f32 v[46:47], v[84:85], v[46:47] op_sel_hi:[0,1]
	v_pk_mul_f32 v[42:43], v[42:43], v[60:61]
	v_pk_mul_f32 v[60:61], v[84:85], v[92:93] op_sel_hi:[0,1]
	v_cvt_pk_bf16_f32 v58, v42, v43
	v_mul_f32_e32 v42, 0xbfb8aa3b, v56
	v_mul_f32_e32 v43, 0xbfb8aa3b, v57
	v_exp_f32_e32 v42, v42
	v_exp_f32_e32 v43, v43
	v_pk_mul_f32 v[28:29], v[64:65], v[28:29] op_sel_hi:[0,1]
	v_pk_mul_f32 v[30:31], v[64:65], v[30:31] op_sel_hi:[0,1]
	v_add_f32_e32 v42, 1.0, v42
	v_add_f32_e32 v43, 1.0, v43
	v_rcp_f32_e32 v42, v42
	v_rcp_f32_e32 v43, v43
	v_pk_mul_f32 v[24:25], v[64:65], v[24:25] op_sel_hi:[0,1]
	v_pk_mul_f32 v[26:27], v[64:65], v[26:27] op_sel_hi:[0,1]
	v_pk_mul_f32 v[42:43], v[42:43], v[56:57]
	s_nop 0
	v_pk_mul_f32 v[42:43], v[42:43], v[60:61]
	s_waitcnt vmcnt(6)
	v_lshlrev_b32_e32 v56, 16, v146
	v_cvt_pk_bf16_f32 v59, v42, v43
	v_lshl_add_u64 v[42:43], v[40:41], 1, v[130:131]
	v_mul_f32_e32 v41, 0xbfb8aa3b, v56
	v_exp_f32_e32 v41, v41
	v_and_b32_e32 v57, 0xffff0000, v146
	global_store_dwordx2 v[42:43], v[58:59], off
	v_lshlrev_b32_e32 v58, 16, v147
	v_add_f32_e32 v41, 1.0, v41
	v_rcp_f32_e32 v60, v41
	v_mul_f32_e32 v41, 0xbfb8aa3b, v57
	v_exp_f32_e32 v41, v41
	v_and_b32_e32 v59, 0xffff0000, v147
	v_add_f32_e32 v41, 1.0, v41
	v_rcp_f32_e32 v61, v41
	v_mul_f32_e32 v41, 0xbfb8aa3b, v58
	v_exp_f32_e32 v41, v41
	v_pk_mul_f32 v[56:57], v[60:61], v[56:57]
	s_nop 0
	v_pk_mul_f32 v[52:53], v[56:57], v[52:53]
	v_add_f32_e32 v41, 1.0, v41
	v_rcp_f32_e32 v56, v41
	v_mul_f32_e32 v41, 0xbfb8aa3b, v59
	v_exp_f32_e32 v41, v41
	v_cvt_pk_bf16_f32 v52, v52, v53
	v_add_f32_e32 v41, 1.0, v41
	v_rcp_f32_e32 v57, v41
	s_nop 0
	v_pk_mul_f32 v[56:57], v[56:57], v[58:59]
	s_nop 0
	v_pk_mul_f32 v[54:55], v[56:57], v[54:55]
	s_nop 0
	v_cvt_pk_bf16_f32 v53, v54, v55
	global_store_dwordx2 v[42:43], v[52:53], off offset:32
	s_waitcnt vmcnt(7)
	v_lshlrev_b32_e32 v52, 16, v144
	v_mul_f32_e32 v41, 0xbfb8aa3b, v52
	v_exp_f32_e32 v41, v41
	v_and_b32_e32 v53, 0xffff0000, v144
	v_lshlrev_b32_e32 v54, 16, v145
	v_and_b32_e32 v55, 0xffff0000, v145
	v_add_f32_e32 v41, 1.0, v41
	v_rcp_f32_e32 v56, v41
	v_mul_f32_e32 v41, 0xbfb8aa3b, v53
	v_exp_f32_e32 v41, v41
	s_nop 0
	v_add_f32_e32 v41, 1.0, v41
	v_rcp_f32_e32 v57, v41
	v_mul_f32_e32 v41, 0xbfb8aa3b, v54
	v_exp_f32_e32 v41, v41
	v_pk_mul_f32 v[52:53], v[56:57], v[52:53]
	s_nop 0
	v_pk_mul_f32 v[48:49], v[52:53], v[48:49]
	v_add_f32_e32 v41, 1.0, v41
	v_rcp_f32_e32 v52, v41
	v_mul_f32_e32 v41, 0xbfb8aa3b, v55
	v_exp_f32_e32 v41, v41
	v_cvt_pk_bf16_f32 v48, v48, v49
	v_add_f32_e32 v41, 1.0, v41
	v_rcp_f32_e32 v53, v41
	s_nop 0
	v_pk_mul_f32 v[52:53], v[52:53], v[54:55]
	s_nop 0
	v_pk_mul_f32 v[50:51], v[52:53], v[50:51]
	s_nop 0
	v_cvt_pk_bf16_f32 v49, v50, v51
	global_store_dwordx2 v[42:43], v[48:49], off offset:64
	s_waitcnt vmcnt(7)
	v_lshlrev_b32_e32 v48, 16, v142
	v_mul_f32_e32 v41, 0xbfb8aa3b, v48
	v_exp_f32_e32 v41, v41
	v_and_b32_e32 v49, 0xffff0000, v142
	v_lshlrev_b32_e32 v50, 16, v143
	v_and_b32_e32 v51, 0xffff0000, v143
	v_add_f32_e32 v41, 1.0, v41
	v_rcp_f32_e32 v52, v41
	v_mul_f32_e32 v41, 0xbfb8aa3b, v49
	v_exp_f32_e32 v41, v41
	s_nop 0
	v_add_f32_e32 v41, 1.0, v41
	v_rcp_f32_e32 v53, v41
	v_mul_f32_e32 v41, 0xbfb8aa3b, v50
	v_exp_f32_e32 v41, v41
	v_pk_mul_f32 v[48:49], v[52:53], v[48:49]
	s_nop 0
	v_pk_mul_f32 v[44:45], v[48:49], v[44:45]
	v_add_f32_e32 v41, 1.0, v41
	v_rcp_f32_e32 v48, v41
	v_mul_f32_e32 v41, 0xbfb8aa3b, v51
	v_exp_f32_e32 v41, v41
	v_cvt_pk_bf16_f32 v44, v44, v45
	v_add_f32_e32 v41, 1.0, v41
	v_rcp_f32_e32 v49, v41
	v_ashrrev_i32_e32 v41, 31, v40
	v_lshl_add_u64 v[40:41], v[40:41], 1, s[28:29]
	v_lshl_add_u64 v[40:41], v[40:41], 0, s[0:1]
	v_pk_mul_f32 v[48:49], v[48:49], v[50:51]
	s_nop 0
	v_pk_mul_f32 v[46:47], v[48:49], v[46:47]
	s_nop 0
	v_cvt_pk_bf16_f32 v45, v46, v47
	global_store_dwordx2 v[42:43], v[44:45], off offset:96
	s_waitcnt vmcnt(7)
; DI unsigned pack2(float a, float b) { fl2_t v = {a, b}; return __builtin_bit_cast(unsigned, __builtin_convertvector(v, bf2_t)); }
; DI float bflo(unsigned u) { return __uint_as_float(u << 16); }
; DI float bfhi(unsigned u) { return __uint_as_float(u & 0xffff0000u); }
; DI float silu_f(float x) { return x * __builtin_amdgcn_rcpf(1.f + __expf(-x)); }
; PH void attn_prompt_item(const Params& p, int layer, int item) {
;     ...
; #pragma unroll
;     for (int qt = 0; qt < 2; ++qt) {
;       const int qi = q0 + qt * 16 + l15;
;       const size_t row = (size_t)(b * 2048 + nb * 128 + qi);
; #pragma unroll
;       for (int dt = 0; dt < 4; ++dt) {
;         const int col = h * 64 + dt * 16 + quad * 4;
;         const uint2 gv = gpre[qt][dt];
;         const float g0 = bflo(gv.x), g1 = bfhi(gv.x), g2 = bflo(gv.y), g3 = bfhi(gv.y);
;         uint2 ov;
;         ov.x = pack2(o[dt][qt][0] * inv[qt] * silu_f(g0), o[dt][qt][1] * inv[qt] * silu_f(g1));
;         ov.y = pack2(o[dt][qt][2] * inv[qt] * silu_f(g2), o[dt][qt][3] * inv[qt] * silu_f(g3));
;         *(uint2*)(MIX + row * 2048 + col) = ov;
;       }
;     }
;   }
	v_lshlrev_b32_e32 v42, 16, v140
	v_and_b32_e32 v43, 0xffff0000, v140
	v_mul_f32_e32 v46, 0xbfb8aa3b, v42
	v_mul_f32_e32 v47, 0xbfb8aa3b, v43
	v_exp_f32_e32 v46, v46
	v_exp_f32_e32 v47, v47
	v_lshlrev_b32_e32 v44, 16, v141
	v_and_b32_e32 v45, 0xffff0000, v141
	v_add_f32_e32 v46, 1.0, v46
	v_add_f32_e32 v47, 1.0, v47
	v_rcp_f32_e32 v46, v46
	v_rcp_f32_e32 v47, v47
	s_nop 0
	v_pk_mul_f32 v[42:43], v[46:47], v[42:43]
	s_nop 0
	v_pk_mul_f32 v[36:37], v[42:43], v[36:37]
	s_nop 0
	v_cvt_pk_bf16_f32 v36, v36, v37
	v_mul_f32_e32 v37, 0xbfb8aa3b, v44
	v_exp_f32_e32 v37, v37
	s_nop 0
	v_add_f32_e32 v37, 1.0, v37
	v_rcp_f32_e32 v42, v37
	v_mul_f32_e32 v37, 0xbfb8aa3b, v45
	v_exp_f32_e32 v37, v37
	s_nop 0
	v_add_f32_e32 v37, 1.0, v37
	v_rcp_f32_e32 v43, v37
	s_nop 0
	v_pk_mul_f32 v[42:43], v[42:43], v[44:45]
	s_nop 0
	v_pk_mul_f32 v[38:39], v[42:43], v[38:39]
	s_nop 0
	v_cvt_pk_bf16_f32 v37, v38, v39
	v_lshl_add_u64 v[38:39], v[120:121], 1, v[40:41]
	global_store_dwordx2 v[38:39], v[36:37], off
	s_waitcnt vmcnt(7)
	v_lshlrev_b32_e32 v36, 16, v138
	v_and_b32_e32 v37, 0xffff0000, v138
	v_mul_f32_e32 v42, 0xbfb8aa3b, v36
	v_mul_f32_e32 v43, 0xbfb8aa3b, v37
	v_exp_f32_e32 v42, v42
	v_exp_f32_e32 v43, v43
	v_lshlrev_b32_e32 v38, 16, v139
	v_and_b32_e32 v39, 0xffff0000, v139
	v_add_f32_e32 v42, 1.0, v42
	v_add_f32_e32 v43, 1.0, v43
	v_rcp_f32_e32 v42, v42
	v_rcp_f32_e32 v43, v43
	s_nop 0
	v_pk_mul_f32 v[36:37], v[42:43], v[36:37]
	s_nop 0
	v_pk_mul_f32 v[32:33], v[36:37], v[32:33]
	s_nop 0
	v_cvt_pk_bf16_f32 v32, v32, v33
	v_mul_f32_e32 v33, 0xbfb8aa3b, v38
	v_exp_f32_e32 v33, v33
	s_nop 0
	v_add_f32_e32 v33, 1.0, v33
	v_rcp_f32_e32 v36, v33
	v_mul_f32_e32 v33, 0xbfb8aa3b, v39
	v_exp_f32_e32 v33, v33
	s_nop 0
	v_add_f32_e32 v33, 1.0, v33
	v_rcp_f32_e32 v37, v33
	s_nop 0
	v_pk_mul_f32 v[36:37], v[36:37], v[38:39]
	s_nop 0
	v_pk_mul_f32 v[34:35], v[36:37], v[34:35]
	s_nop 0
	v_cvt_pk_bf16_f32 v33, v34, v35
	v_lshl_add_u64 v[34:35], v[122:123], 1, v[40:41]
	global_store_dwordx2 v[34:35], v[32:33], off
	s_waitcnt vmcnt(7)
	v_lshlrev_b32_e32 v32, 16, v136
	v_and_b32_e32 v33, 0xffff0000, v136
	v_mul_f32_e32 v36, 0xbfb8aa3b, v32
	v_mul_f32_e32 v37, 0xbfb8aa3b, v33
	v_exp_f32_e32 v36, v36
	v_exp_f32_e32 v37, v37
	v_lshlrev_b32_e32 v34, 16, v137
	v_and_b32_e32 v35, 0xffff0000, v137
	v_add_f32_e32 v36, 1.0, v36
	v_add_f32_e32 v37, 1.0, v37
	v_rcp_f32_e32 v36, v36
	v_rcp_f32_e32 v37, v37
	s_nop 0
	v_pk_mul_f32 v[32:33], v[36:37], v[32:33]
	s_nop 0
	v_pk_mul_f32 v[28:29], v[32:33], v[28:29]
	v_mov_b64_e32 v[38:39], v[14:15]
	v_cvt_pk_bf16_f32 v28, v28, v29
	v_mul_f32_e32 v29, 0xbfb8aa3b, v34
	v_exp_f32_e32 v29, v29
	v_mov_b64_e32 v[36:37], v[12:13]
	v_add_f32_e32 v29, 1.0, v29
	v_rcp_f32_e32 v32, v29
	v_mul_f32_e32 v29, 0xbfb8aa3b, v35
	v_exp_f32_e32 v29, v29
	s_nop 0
	v_add_f32_e32 v29, 1.0, v29
	v_rcp_f32_e32 v33, v29
	s_nop 0
	v_pk_mul_f32 v[32:33], v[32:33], v[34:35]
	s_nop 0
	v_pk_mul_f32 v[30:31], v[32:33], v[30:31]
	s_nop 0
	v_cvt_pk_bf16_f32 v29, v30, v31
	v_lshl_add_u64 v[30:31], v[124:125], 1, v[40:41]
	global_store_dwordx2 v[30:31], v[28:29], off
	s_waitcnt vmcnt(7)
	v_lshlrev_b32_e32 v28, 16, v134
	v_and_b32_e32 v29, 0xffff0000, v134
	v_mul_f32_e32 v32, 0xbfb8aa3b, v28
	v_mul_f32_e32 v33, 0xbfb8aa3b, v29
	v_exp_f32_e32 v32, v32
	v_exp_f32_e32 v33, v33
	v_lshlrev_b32_e32 v30, 16, v135
	v_and_b32_e32 v31, 0xffff0000, v135
	v_add_f32_e32 v32, 1.0, v32
	v_add_f32_e32 v33, 1.0, v33
	v_rcp_f32_e32 v32, v32
	v_rcp_f32_e32 v33, v33
	s_nop 0
	v_pk_mul_f32 v[28:29], v[32:33], v[28:29]
	s_nop 0
	v_pk_mul_f32 v[24:25], v[28:29], v[24:25]
	v_mov_b64_e32 v[34:35], v[22:23]
	v_cvt_pk_bf16_f32 v24, v24, v25
	v_mul_f32_e32 v25, 0xbfb8aa3b, v30
	v_exp_f32_e32 v25, v25
	v_mov_b64_e32 v[32:33], v[20:21]
	v_add_f32_e32 v25, 1.0, v25
	v_rcp_f32_e32 v28, v25
	v_mul_f32_e32 v25, 0xbfb8aa3b, v31
	v_exp_f32_e32 v25, v25
	s_nop 0
	v_add_f32_e32 v25, 1.0, v25
	v_rcp_f32_e32 v29, v25
	s_nop 0
	v_pk_mul_f32 v[28:29], v[28:29], v[30:31]
	s_nop 0
	v_pk_mul_f32 v[26:27], v[28:29], v[26:27]
	v_mov_b64_e32 v[30:31], v[6:7]
	v_cvt_pk_bf16_f32 v25, v26, v27
	v_lshl_add_u64 v[26:27], v[126:127], 1, v[40:41]
	global_store_dwordx2 v[26:27], v[24:25], off
	v_mov_b64_e32 v[26:27], v[18:19]
	v_mov_b64_e32 v[42:43], v[10:11]
	v_mov_b64_e32 v[24:25], v[16:17]
	v_mov_b64_e32 v[40:41], v[8:9]
	v_mov_b64_e32 v[28:29], v[4:5]
	s_cbranch_scc1 .LBB0_286

; PH void attn_prompt_item(const Params& p, int layer, int item) {
;     ...
;   }
; }
.LBB0_286:
	s_nop 0
	s_nop 0
	s_nop 0
	s_nop 0
	s_nop 0
	s_nop 0
	s_nop 0
	s_nop 0
	s_nop 0
	s_nop 0
	s_nop 0
	s_nop 0
	s_nop 0
	s_nop 0
	s_nop 0
	s_nop 0
	s_nop 0
	s_nop 0
	s_nop 0
	s_nop 0
	s_nop 0
	s_nop 0
	s_nop 0
	s_nop 0
	s_nop 0
	s_nop 0
	s_nop 0
	s_nop 0
	s_nop 0
	s_nop 0
	s_nop 0
	s_nop 0
	s_nop 0
	s_nop 0
	s_nop 0
	s_nop 0
	s_nop 0
	s_nop 0
	s_nop 0
	s_nop 0
	s_nop 0
	s_nop 0
	s_nop 0
	s_nop 0
	s_nop 0
	s_nop 0
	s_nop 0
	s_nop 0
	s_nop 0
	s_nop 0
	s_nop 0
	s_nop 0
	s_nop 0
	s_nop 0
	s_nop 0
	s_nop 0
	s_mov_b64 s[0:1], 0

; template <int PROBE, int SONLY, int CPS>
; DI void ssd_chunk_loop(const Params& p, int layer, int b, int e, int c0, f32x4 (&h)[8], float& dtot, bool write_final) {
;     ...
;     {
;       const int nb_ = b * 2048 + ((cc + 1 < c0 + CPS) ? (cc + 1) : cc) * 64;
; #pragma unroll
;       for (int i = 0; i < 4; ++i) {
;         const int idx = tid + 256 * i, r = idx >> 4, c16 = idx & 15;
;         if (!SONLY) pc[i] = *(const u32x4*)(XBC + (size_t)(nb_ + r) * 1280 + 1024 + g * 128 + c16 * 8);
;         pb[i] = *(const u32x4*)(XBC + (size_t)(nb_ + r) * 1280 + 768 + g * 128 + c16 * 8);
;       }
; #pragma unroll
;       for (int i = 0; i < 2; ++i) {
;         const int idx = tid + 256 * i, r = idx >> 3, c8 = idx & 7;
;         px[i] = *(const u32x4*)(XBC + (size_t)(nb_ + r) * 1280 + e * 64 + c8 * 8);
;       }
;       pru = PROJ[(size_t)(nb_ + lane) * NPAD + C_DT + e];
;     }
;     uint2 dx[4], dz[4];
;     if (!SONLY)
; #pragma unroll
;     for (int qt = 0; qt < 4; ++qt) {
;       const size_t row = (size_t)(base + qt * 16 + l15);
;       const int pcol = w * 16 + quad * 4;
;       dx[qt] = *(const uint2*)(XBC + row * 1280 + e * 64 + pcol);
;       dz[qt] = *(const uint2*)(PROJ + row * NPAD + C_Z + e * 64 + pcol);
;     }
;     __syncthreads();
;     dtot += acs_s[63];
;     if (!(PROBE & 2)) {
; #pragma unroll
;     for (int i = 0; i < 2; ++i) {
;       const int idx = tid + 256 * i, r = idx >> 3, c8 = idx & 7;
;       const float dtv = dt_s[r];
;       float f[8]; unpack8v(xr[i], f);
; #pragma unroll
;       for (int j = 0; j < 8; ++j) Xt[(c8 * 8 + j) * 72 + r] = f2bf(f[j] * dtv);
;     }
.LBB0_515:
	s_or_b64 exec, exec, s[84:85]
	s_cmpk_lg_i32 s13, 0x800
	s_cselect_b32 s2, s13, 0x7c0
	s_add_i32 s2, s2, s87
	v_or_b32_e32 v114, s2, v133
	v_mov_b64_e32 v[112:113], s[4:5]
	v_add_u32_e32 v124, s13, v242
	v_mad_u64_u32 v[114:115], s[6:7], v114, s97, v[112:113]
	s_mov_b32 s9, s3
	v_subrev_u32_e32 v160, 64, v124
	v_add_u32_e32 v32, s2, v175
	v_add_u32_e32 v40, s2, v177
	v_add_u32_e32 v48, s2, v178
	v_add_u32_e32 v56, s2, v179
	v_add_u32_e32 v96, s2, v176
	v_add_u32_e32 v98, s2, v180
	v_lshl_add_u64 v[114:115], v[114:115], 0, s[8:9]
	v_mad_u64_u32 v[118:119], s[6:7], v160, s97, v[112:113]
	s_lshl_b32 s2, s22, 1
	v_add_co_u32_e32 v114, vcc, s16, v114
	v_lshl_add_u64 v[118:119], v[118:119], 0, s[2:3]
	v_lshlrev_b64 v[120:121], 1, v[134:135]
	v_addc_co_u32_e32 v115, vcc, 0, v115, vcc
	v_lshl_add_u64 v[118:119], v[118:119], 0, v[120:121]
	v_mad_i64_i32 v[36:37], s[6:7], v32, s34, v[146:147]
	v_mad_i64_i32 v[44:45], s[6:7], v40, s34, v[146:147]
	v_mad_i64_i32 v[52:53], s[6:7], v48, s34, v[146:147]
	v_mad_i64_i32 v[60:61], s[6:7], v56, s34, v[146:147]
	v_mad_i64_i32 v[96:97], s[6:7], v96, s34, v[130:131]
	v_mad_i64_i32 v[100:101], s[6:7], v98, s34, v[130:131]
	v_add_co_u32_e32 v118, vcc, s10, v118
	v_subrev_u32_e32 v164, 48, v124
	global_load_dwordx4 v[32:35], v[36:37], off offset:2048
	s_nop 0
	global_load_dwordx4 v[36:39], v[36:37], off offset:1536
	s_nop 0
	global_load_dwordx4 v[40:43], v[44:45], off offset:2048
	s_nop 0
	global_load_dwordx4 v[44:47], v[44:45], off offset:1536
	s_nop 0
	global_load_dwordx4 v[48:51], v[52:53], off offset:2048
	s_nop 0
	global_load_dwordx4 v[52:55], v[52:53], off offset:1536
	s_nop 0
	global_load_dwordx4 v[56:59], v[60:61], off offset:2048
	s_nop 0
	global_load_dwordx4 v[60:63], v[60:61], off offset:1536
	s_nop 0
	global_load_dwordx4 v[96:99], v[96:97], off
	s_nop 0
	global_load_dwordx4 v[100:103], v[100:101], off
	v_mad_u64_u32 v[116:117], s[6:7], v160, s34, v[136:137]
	v_addc_co_u32_e32 v119, vcc, 0, v119, vcc
	v_mad_u64_u32 v[122:123], s[6:7], v164, s34, v[136:137]
	global_load_ushort v163, v[114:115], off offset:1536
	global_load_dwordx2 v[172:173], v[116:117], off
	global_load_dwordx2 v[170:171], v[118:119], off offset:1536
	global_load_dwordx2 v[166:167], v[122:123], off
	v_mad_u64_u32 v[114:115], s[6:7], v164, s97, v[112:113]
	v_lshl_add_u64 v[114:115], v[114:115], 0, s[2:3]
	v_subrev_u32_e32 v154, 32, v124
	v_lshl_add_u64 v[114:115], v[114:115], 0, v[120:121]
	v_mad_u64_u32 v[118:119], s[6:7], v154, s97, v[112:113]
	v_add_co_u32_e32 v114, vcc, s10, v114
	v_lshl_add_u64 v[118:119], v[118:119], 0, s[2:3]
	v_add_u32_e32 v148, -16, v124
	v_addc_co_u32_e32 v115, vcc, 0, v115, vcc
	v_lshl_add_u64 v[118:119], v[118:119], 0, v[120:121]
	v_mad_u64_u32 v[112:113], s[6:7], v148, s97, v[112:113]
	v_add_co_u32_e32 v118, vcc, s10, v118
	v_lshl_add_u64 v[112:113], v[112:113], 0, s[2:3]
	s_nop 0
	v_addc_co_u32_e32 v119, vcc, 0, v119, vcc
	v_lshl_add_u64 v[112:113], v[112:113], 0, v[120:121]
	v_add_co_u32_e32 v112, vcc, s10, v112
	v_mad_u64_u32 v[116:117], s[6:7], v154, s34, v[136:137]
	s_nop 0
	v_addc_co_u32_e32 v113, vcc, 0, v113, vcc
	v_mad_u64_u32 v[122:123], s[6:7], v148, s34, v[136:137]
	global_load_dwordx2 v[168:169], v[114:115], off offset:1536
	global_load_dwordx2 v[158:159], v[116:117], off
	global_load_dwordx2 v[156:157], v[118:119], off offset:1536
	global_load_dwordx2 v[150:151], v[122:123], off
	global_load_dwordx2 v[152:153], v[112:113], off offset:1536
	s_waitcnt lgkmcnt(0)
	s_barrier
	ds_read_b32 v113, v219
	s_waitcnt vmcnt(21)
	v_lshlrev_b32_e32 v114, 16, v108
	v_and_b32_e32 v108, 0xffff0000, v108
	v_mov_b32_e32 v112, s20
	v_lshlrev_b32_e32 v115, 16, v109
	s_waitcnt lgkmcnt(0)
	v_mul_f32_e32 v108, v113, v108
	v_cvt_pk_bf16_f32 v108, v108, s0
	ds_read_b32 v112, v112
	ds_read_b32 v118, v220
	ds_read_b32 v119, v205
	ds_write_b16 v243, v108 offset:53392
	v_mul_f32_e32 v108, v113, v115
	v_and_b32_e32 v109, 0xffff0000, v109
	v_cvt_pk_bf16_f32 v108, v108, s0
	ds_write_b16 v243, v108 offset:53536
	v_mul_f32_e32 v108, v113, v109
	v_lshlrev_b32_e32 v116, 16, v110
	v_cvt_pk_bf16_f32 v108, v108, s0
	ds_write_b16 v243, v108 offset:53680
	v_mul_f32_e32 v108, v113, v116
	v_and_b32_e32 v110, 0xffff0000, v110
	v_cvt_pk_bf16_f32 v108, v108, s0
	ds_write_b16 v243, v108 offset:53824
	v_mul_f32_e32 v108, v113, v110
	v_lshlrev_b32_e32 v117, 16, v111
	v_cvt_pk_bf16_f32 v108, v108, s0
	ds_write_b16 v243, v108 offset:53968
	v_mul_f32_e32 v108, v113, v117
	v_and_b32_e32 v111, 0xffff0000, v111
	v_cvt_pk_bf16_f32 v108, v108, s0
	ds_write_b16 v243, v108 offset:54112
	v_mul_f32_e32 v108, v113, v111
	v_cvt_pk_bf16_f32 v108, v108, s0
	ds_write_b16 v243, v108 offset:54256
	s_waitcnt vmcnt(20)
	v_lshlrev_b32_e32 v108, 16, v104
	v_and_b32_e32 v104, 0xffff0000, v104
	v_mul_f32_e32 v114, v113, v114
	s_waitcnt lgkmcnt(8)
	v_mul_f32_e32 v104, v118, v104
	v_cvt_pk_bf16_f32 v114, v114, s0
	v_lshlrev_b32_e32 v109, 16, v105
	v_cvt_pk_bf16_f32 v104, v104, s0
	ds_write_b16 v243, v114 offset:53248
	ds_write_b16 v244, v104 offset:53392
	v_mul_f32_e32 v104, v118, v109
	v_and_b32_e32 v105, 0xffff0000, v105
	v_cvt_pk_bf16_f32 v104, v104, s0
	ds_write_b16 v244, v104 offset:53536
	v_mul_f32_e32 v104, v118, v105
	v_lshlrev_b32_e32 v110, 16, v106
	v_cvt_pk_bf16_f32 v104, v104, s0
	ds_write_b16 v244, v104 offset:53680
	v_mul_f32_e32 v104, v118, v110
	v_and_b32_e32 v106, 0xffff0000, v106
	v_cvt_pk_bf16_f32 v104, v104, s0
	ds_write_b16 v244, v104 offset:53824
	v_mul_f32_e32 v104, v118, v106
	v_lshlrev_b32_e32 v111, 16, v107
	v_cvt_pk_bf16_f32 v104, v104, s0
	ds_write_b16 v244, v104 offset:53968
	v_mul_f32_e32 v104, v118, v111
	v_and_b32_e32 v107, 0xffff0000, v107
	v_cvt_pk_bf16_f32 v104, v104, s0
	v_mul_f32_e32 v108, v118, v108
	ds_write_b16 v244, v104 offset:54112
	v_mul_f32_e32 v104, v118, v107
	v_cvt_pk_bf16_f32 v108, v108, s0
	v_cvt_pk_bf16_f32 v104, v104, s0
	ds_write_b16 v244, v108 offset:53248
	ds_write_b16 v244, v104 offset:54256
	v_add_u32_e32 v107, v206, v207
	s_waitcnt lgkmcnt(14)
; DI float bflo(unsigned u) { return __uint_as_float(u << 16); }
; DI float bfhi(unsigned u) { return __uint_as_float(u & 0xffff0000u); }
; DI f32x4 mfma16(bf16x8 a, bf16x8 b, f32x4 c) { return __builtin_amdgcn_mfma_f32_16x16x32_bf16(a, b, c, 0, 0, 0); }
; template <int PROBE, int SONLY, int CPS>
; DI void ssd_chunk_loop(const Params& p, int layer, int b, int e, int c0, f32x4 (&h)[8], float& dtot, bool write_final) {
;     ...
;     {
;       const int q = tid & 63, ng = tid >> 6;
;       const float dte = __expf(acs_s[63] - acs_s[q]);
; #pragma unroll
;       for (int i = 0; i < 8; ++i) {
;         const uint2 v = *(const uint2*)(Bs + q * 136 + ng * 32 + i * 4);
;         Bt2[(ng * 32 + i * 4 + 0) * 72 + q] = f2bf(bflo(v.x) * dte);
;         Bt2[(ng * 32 + i * 4 + 1) * 72 + q] = f2bf(bfhi(v.x) * dte);
;         Bt2[(ng * 32 + i * 4 + 2) * 72 + q] = f2bf(bflo(v.y) * dte);
;         Bt2[(ng * 32 + i * 4 + 3) * 72 + q] = f2bf(bfhi(v.y) * dte);
;       }
;     }
;     }
;     __syncthreads();
;     if (!(PROBE & 4) && !SONLY) {
;       const int q = w * 16 + l15;
;       const float aq = acs_s[q];
;       bf16x8 cfr[4];
; #pragma unroll
;       for (int ks = 0; ks < 4; ++ks) cfr[ks] = ldfrag(Cs, 136, w * 16, ks * 32, lane);
; #pragma unroll
;       for (int st = 0; st < 4; ++st) {
;         uint2 ov;
;         const int s0 = st * 16 + quad * 4;
;         {
;           f32x4 acc = (f32x4){0.f, 0.f, 0.f, 0.f};
; #pragma unroll
;           for (int ks = 0; ks < 4; ++ks) acc = mfma16(ldfrag(Bs, 136, st * 16, ks * 32, lane), cfr[ks], acc);
;           float v[4];
; #pragma unroll
;           for (int r = 0; r < 4; ++r) { const int s = s0 + r; v[r] = (s <= q) ? acc[r] * __expf(fminf(aq - acs_s[s], 0.f)) : 0.f; }
	v_sub_f32_e32 v106, v112, v119
	ds_read_b64 v[104:105], v107 offset:17408
	v_mul_f32_e32 v106, 0x3fb8aa3b, v106
	v_exp_f32_e32 v106, v106
	v_add_u32_e32 v125, v210, v223
	v_mov_b32_e32 v127, 0
	s_waitcnt lgkmcnt(0)
	v_lshlrev_b32_e32 v108, 16, v104
	v_and_b32_e32 v104, 0xffff0000, v104
	v_mul_f32_e32 v108, v106, v108
	v_mul_f32_e32 v104, v106, v104
	v_cvt_pk_bf16_f32 v108, v108, s0
	v_cvt_pk_bf16_f32 v104, v104, s0
	ds_write_b16 v221, v108 offset:34816
	ds_write_b16 v222, v104 offset:34960
	v_lshlrev_b32_e32 v104, 16, v105
	v_mul_f32_e32 v104, v106, v104
	v_cvt_pk_bf16_f32 v104, v104, s0
	ds_write_b16 v222, v104 offset:35104
	v_and_b32_e32 v104, 0xffff0000, v105
	v_mul_f32_e32 v104, v106, v104
	v_cvt_pk_bf16_f32 v104, v104, s0
	ds_write_b16 v222, v104 offset:35248
	ds_read_b64 v[104:105], v107 offset:17416
	v_mov_b32_e32 v149, 0
	s_waitcnt lgkmcnt(0)
	v_lshlrev_b32_e32 v108, 16, v104
	v_and_b32_e32 v104, 0xffff0000, v104
	v_mul_f32_e32 v108, v106, v108
	v_mul_f32_e32 v104, v106, v104
	v_cvt_pk_bf16_f32 v108, v108, s0
	v_cvt_pk_bf16_f32 v104, v104, s0
	ds_write_b16 v221, v108 offset:35392
	ds_write_b16 v222, v104 offset:35536
	v_lshlrev_b32_e32 v104, 16, v105
	v_mul_f32_e32 v104, v106, v104
	v_cvt_pk_bf16_f32 v104, v104, s0
	ds_write_b16 v222, v104 offset:35680
	v_and_b32_e32 v104, 0xffff0000, v105
	v_mul_f32_e32 v104, v106, v104
	v_cvt_pk_bf16_f32 v104, v104, s0
	ds_write_b16 v222, v104 offset:35824
	ds_read_b64 v[104:105], v107 offset:17424
	s_waitcnt lgkmcnt(0)
	v_lshlrev_b32_e32 v108, 16, v104
	v_and_b32_e32 v104, 0xffff0000, v104
	v_mul_f32_e32 v108, v106, v108
	v_mul_f32_e32 v104, v106, v104
	v_cvt_pk_bf16_f32 v108, v108, s0
	v_cvt_pk_bf16_f32 v104, v104, s0
	ds_write_b16 v221, v108 offset:35968
	ds_write_b16 v222, v104 offset:36112
	v_lshlrev_b32_e32 v104, 16, v105
	v_mul_f32_e32 v104, v106, v104
	v_cvt_pk_bf16_f32 v104, v104, s0
	ds_write_b16 v222, v104 offset:36256
	v_and_b32_e32 v104, 0xffff0000, v105
	v_mul_f32_e32 v104, v106, v104
	v_cvt_pk_bf16_f32 v104, v104, s0
	ds_write_b16 v222, v104 offset:36400
	ds_read_b64 v[104:105], v107 offset:17432
	s_waitcnt lgkmcnt(0)
	v_lshlrev_b32_e32 v108, 16, v104
	v_and_b32_e32 v104, 0xffff0000, v104
	v_mul_f32_e32 v108, v106, v108
	v_mul_f32_e32 v104, v106, v104
	v_cvt_pk_bf16_f32 v108, v108, s0
	v_cvt_pk_bf16_f32 v104, v104, s0
	ds_write_b16 v221, v108 offset:36544
	ds_write_b16 v222, v104 offset:36688
	v_lshlrev_b32_e32 v104, 16, v105
	v_mul_f32_e32 v104, v106, v104
	v_cvt_pk_bf16_f32 v104, v104, s0
	ds_write_b16 v222, v104 offset:36832
	v_and_b32_e32 v104, 0xffff0000, v105
	v_mul_f32_e32 v104, v106, v104
	v_cvt_pk_bf16_f32 v104, v104, s0
	ds_write_b16 v222, v104 offset:36976
	ds_read_b64 v[104:105], v107 offset:17440
	s_waitcnt lgkmcnt(0)
	v_lshlrev_b32_e32 v108, 16, v104
	v_and_b32_e32 v104, 0xffff0000, v104
	v_mul_f32_e32 v108, v106, v108
	v_mul_f32_e32 v104, v106, v104
	v_cvt_pk_bf16_f32 v108, v108, s0
	v_cvt_pk_bf16_f32 v104, v104, s0
	ds_write_b16 v221, v108 offset:37120
	ds_write_b16 v222, v104 offset:37264
	v_lshlrev_b32_e32 v104, 16, v105
	v_mul_f32_e32 v104, v106, v104
	v_cvt_pk_bf16_f32 v104, v104, s0
	ds_write_b16 v222, v104 offset:37408
	v_and_b32_e32 v104, 0xffff0000, v105
	v_mul_f32_e32 v104, v106, v104
	v_cvt_pk_bf16_f32 v104, v104, s0
	ds_write_b16 v222, v104 offset:37552
	ds_read_b64 v[104:105], v107 offset:17448
	s_waitcnt lgkmcnt(0)
	v_lshlrev_b32_e32 v108, 16, v104
	v_and_b32_e32 v104, 0xffff0000, v104
	v_mul_f32_e32 v108, v106, v108
	v_mul_f32_e32 v104, v106, v104
	v_cvt_pk_bf16_f32 v108, v108, s0
	v_cvt_pk_bf16_f32 v104, v104, s0
	ds_write_b16 v221, v108 offset:37696
	ds_write_b16 v222, v104 offset:37840
	v_lshlrev_b32_e32 v104, 16, v105
	v_mul_f32_e32 v104, v106, v104
	v_cvt_pk_bf16_f32 v104, v104, s0
	ds_write_b16 v222, v104 offset:37984
	v_and_b32_e32 v104, 0xffff0000, v105
	v_mul_f32_e32 v104, v106, v104
	v_cvt_pk_bf16_f32 v104, v104, s0
	ds_write_b16 v222, v104 offset:38128
	ds_read_b64 v[104:105], v107 offset:17456
	s_waitcnt lgkmcnt(0)
	v_lshlrev_b32_e32 v108, 16, v104
	v_and_b32_e32 v104, 0xffff0000, v104
	v_mul_f32_e32 v108, v106, v108
	v_mul_f32_e32 v104, v106, v104
	v_cvt_pk_bf16_f32 v108, v108, s0
	v_cvt_pk_bf16_f32 v104, v104, s0
	ds_write_b16 v221, v108 offset:38272
	ds_write_b16 v222, v104 offset:38416
	v_lshlrev_b32_e32 v104, 16, v105
	v_mul_f32_e32 v104, v106, v104
	v_cvt_pk_bf16_f32 v104, v104, s0
	ds_write_b16 v222, v104 offset:38560
	v_and_b32_e32 v104, 0xffff0000, v105
	v_mul_f32_e32 v104, v106, v104
	v_cvt_pk_bf16_f32 v104, v104, s0
	ds_write_b16 v222, v104 offset:38704
	ds_read_b64 v[104:105], v107 offset:17464
	s_waitcnt lgkmcnt(0)
	v_lshlrev_b32_e32 v107, 16, v104
	v_and_b32_e32 v104, 0xffff0000, v104
	v_mul_f32_e32 v107, v106, v107
	v_mul_f32_e32 v104, v106, v104
	v_cvt_pk_bf16_f32 v107, v107, s0
	v_cvt_pk_bf16_f32 v104, v104, s0
	ds_write_b16 v221, v107 offset:38848
	ds_write_b16 v222, v104 offset:38992
	v_lshlrev_b32_e32 v104, 16, v105
	v_mul_f32_e32 v104, v106, v104
	v_cvt_pk_bf16_f32 v104, v104, s0
	ds_write_b16 v222, v104 offset:39136
	v_and_b32_e32 v104, 0xffff0000, v105
	v_mul_f32_e32 v104, v106, v104
	v_cvt_pk_bf16_f32 v104, v104, s0
	ds_write_b16 v222, v104 offset:39280
	s_waitcnt lgkmcnt(0)
	s_barrier
	ds_read_b32 v0, v225
	ds_read_b32 v1, v226
	ds_read_b32 v2, v228
	ds_read_b32 v3, v229
	ds_read_b32 v4, v230
	ds_read_b32 v5, v231
	ds_read_b32 v6, v232
	ds_read_b32 v7, v233
	ds_read_b32 v8, v234
	ds_read_b32 v9, v235
	ds_read_b32 v10, v236
	ds_read_b32 v11, v239
	s_waitcnt lgkmcnt(8)
	ds_read_b32 v12, v224
	ds_read_b32 v13, v224 offset:4
	ds_read_b32 v14, v237
	ds_read_b32 v15, v238
	s_waitcnt lgkmcnt(4)
	ds_read_b128 v[104:107], v125 offset:17408
	ds_read_b128 v[108:111], v209
	ds_read_b128 v[116:119], v125 offset:17472
	s_waitcnt lgkmcnt(1)
	v_mfma_f32_16x16x32_bf16 v[120:123], v[104:107], v[108:111], 0
	ds_read_b128 v[248:251], v125 offset:17536
	ds_read_b128 v[112:115], v209 offset:64
	ds_read_b128 v[104:107], v209 offset:128
	s_waitcnt lgkmcnt(1)
	v_mfma_f32_16x16x32_bf16 v[116:119], v[116:119], v[112:115], v[120:123]
	s_nop 2
	ds_read_b128 v[120:123], v125 offset:17600
	s_waitcnt lgkmcnt(1)
	v_mfma_f32_16x16x32_bf16 v[248:251], v[248:251], v[104:107], v[116:119]
	s_nop 2
	ds_read_b128 v[116:119], v209 offset:192
	ds_read_b32 v124, v208
	s_waitcnt lgkmcnt(1)
	v_mfma_f32_16x16x32_bf16 v[120:123], v[120:123], v[116:119], v[248:251]
	s_and_saveexec_b64 s[6:7], s[52:53]
	s_cbranch_execnz .LBB0_553
	s_or_b64 exec, exec, s[6:7]
	s_nop 4
	v_mov_b32_e32 v120, 0
	s_and_saveexec_b64 s[6:7], s[54:55]
	s_cbranch_execnz .LBB0_554

; DI unsigned pack2(float a, float b) { fl2_t v = {a, b}; return __builtin_bit_cast(unsigned, __builtin_convertvector(v, bf2_t)); }
; DI f32x4 mfma16(bf16x8 a, bf16x8 b, f32x4 c) { return __builtin_amdgcn_mfma_f32_16x16x32_bf16(a, b, c, 0, 0, 0); }
; template <int PROBE, int SONLY, int CPS>
; DI void ssd_chunk_loop(const Params& p, int layer, int b, int e, int c0, f32x4 (&h)[8], float& dtot, bool write_final) {
;     ...
;       for (int st = 0; st < 4; ++st) {
;         uint2 ov;
;         const int s0 = st * 16 + quad * 4;
;         {
;           f32x4 acc = (f32x4){0.f, 0.f, 0.f, 0.f};
; #pragma unroll
;           for (int ks = 0; ks < 4; ++ks) acc = mfma16(ldfrag(Bs, 136, st * 16, ks * 32, lane), cfr[ks], acc);
;           float v[4];
; #pragma unroll
;           for (int r = 0; r < 4; ++r) { const int s = s0 + r; v[r] = (s <= q) ? acc[r] * __expf(fminf(aq - acs_s[s], 0.f)) : 0.f; }
;           ov.x = pack2(v[0], v[1]); ov.y = pack2(v[2], v[3]);
;         }
;         *(uint2*)(Ms + q * 72 + s0) = ov;
.LBB0_518:
	s_nop 0
	s_waitcnt lgkmcnt(0)
	v_sub_f32_e32 v121, v124, v0
	v_min_f32_e32 v121, 0, v121
	v_mul_f32_e32 v121, 0x3fb8aa3b, v121
	v_exp_f32_e32 v121, v121
	s_nop 0
	v_mul_f32_e32 v127, v122, v121
.LBB0_519:
	s_or_b64 exec, exec, s[6:7]
	v_mov_b32_e32 v126, 0
	v_mov_b32_e32 v121, 0
	s_and_saveexec_b64 s[6:7], s[58:59]
	s_cbranch_execz .LBB0_521
	s_nop 0
	s_waitcnt lgkmcnt(0)
	v_sub_f32_e32 v121, v124, v1
	v_min_f32_e32 v121, 0, v121
	v_mul_f32_e32 v121, 0x3fb8aa3b, v121
	v_exp_f32_e32 v121, v121
	s_nop 0
	v_mul_f32_e32 v121, v123, v121
.LBB0_521:
	s_or_b64 exec, exec, s[6:7]
	v_cvt_pk_bf16_f32 v120, v149, v120
	v_cvt_pk_bf16_f32 v121, v127, v121
	ds_write_b64 v227, v[120:121] offset:62464
	ds_read_b128 v[120:123], v125 offset:21760
	ds_read_b128 v[248:251], v125 offset:21824
	s_waitcnt lgkmcnt(1)
	v_mfma_f32_16x16x32_bf16 v[120:123], v[120:123], v[108:111], 0
	s_waitcnt lgkmcnt(0)
	v_mfma_f32_16x16x32_bf16 v[120:123], v[248:251], v[112:115], v[120:123]
	ds_read_b128 v[248:251], v125 offset:21888
	s_waitcnt lgkmcnt(0)
	v_mfma_f32_16x16x32_bf16 v[120:123], v[248:251], v[104:107], v[120:123]
	ds_read_b128 v[248:251], v125 offset:21952
	s_waitcnt lgkmcnt(0)
	v_mfma_f32_16x16x32_bf16 v[120:123], v[248:251], v[116:119], v[120:123]
	s_and_saveexec_b64 s[6:7], s[60:61]
	s_cbranch_execz .LBB0_523
	s_nop 0
	s_waitcnt lgkmcnt(0)
	v_sub_f32_e32 v126, v124, v2
	v_min_f32_e32 v126, 0, v126
	v_mul_f32_e32 v126, 0x3fb8aa3b, v126
	v_exp_f32_e32 v126, v126
	s_nop 0
	v_mul_f32_e32 v126, v120, v126
.LBB0_523:
	s_or_b64 exec, exec, s[6:7]
	s_nop 4
	v_mov_b32_e32 v120, 0
	v_mov_b32_e32 v149, 0
	s_and_saveexec_b64 s[6:7], s[62:63]
	s_cbranch_execz .LBB0_525
	s_nop 0
	s_waitcnt lgkmcnt(0)
	v_sub_f32_e32 v127, v124, v3
	v_min_f32_e32 v127, 0, v127
	v_mul_f32_e32 v127, 0x3fb8aa3b, v127
	v_exp_f32_e32 v127, v127
	s_nop 0
	v_mul_f32_e32 v149, v121, v127
.LBB0_525:
	s_or_b64 exec, exec, s[6:7]
	s_and_saveexec_b64 s[6:7], s[64:65]
	s_cbranch_execz .LBB0_527
	s_nop 0
	s_waitcnt lgkmcnt(0)
	v_sub_f32_e32 v120, v124, v4
	v_min_f32_e32 v120, 0, v120
	v_mul_f32_e32 v120, 0x3fb8aa3b, v120
	v_exp_f32_e32 v120, v120
	s_nop 0
	v_mul_f32_e32 v120, v122, v120
.LBB0_527:
	s_or_b64 exec, exec, s[6:7]
	v_mov_b32_e32 v127, 0
	v_mov_b32_e32 v121, 0
	s_and_saveexec_b64 s[6:7], s[66:67]
	s_cbranch_execz .LBB0_529
	s_nop 0
	s_waitcnt lgkmcnt(0)
	v_sub_f32_e32 v121, v124, v5
	v_min_f32_e32 v121, 0, v121
	v_mul_f32_e32 v121, 0x3fb8aa3b, v121
	v_exp_f32_e32 v121, v121
	s_nop 0
	v_mul_f32_e32 v121, v123, v121
.LBB0_529:
	s_or_b64 exec, exec, s[6:7]
	v_cvt_pk_bf16_f32 v122, v126, v149
	v_cvt_pk_bf16_f32 v123, v120, v121
	ds_write_b64 v227, v[122:123] offset:62496
	ds_read_b128 v[120:123], v125 offset:26112
	ds_read_b128 v[248:251], v125 offset:26176
	s_waitcnt lgkmcnt(1)
	v_mfma_f32_16x16x32_bf16 v[120:123], v[120:123], v[108:111], 0
	s_waitcnt lgkmcnt(0)
	v_mfma_f32_16x16x32_bf16 v[120:123], v[248:251], v[112:115], v[120:123]
	ds_read_b128 v[248:251], v125 offset:26240
	s_waitcnt lgkmcnt(0)
	v_mfma_f32_16x16x32_bf16 v[120:123], v[248:251], v[104:107], v[120:123]
	ds_read_b128 v[248:251], v125 offset:26304
	s_waitcnt lgkmcnt(0)
	v_mfma_f32_16x16x32_bf16 v[120:123], v[248:251], v[116:119], v[120:123]
	s_and_saveexec_b64 s[6:7], s[68:69]
	s_cbranch_execz .LBB0_531
	s_nop 0
	s_waitcnt lgkmcnt(0)
	v_sub_f32_e32 v126, v124, v6
	v_min_f32_e32 v126, 0, v126
	v_mul_f32_e32 v126, 0x3fb8aa3b, v126
	v_exp_f32_e32 v126, v126
	s_nop 0
	v_mul_f32_e32 v127, v120, v126
.LBB0_531:
	s_or_b64 exec, exec, s[6:7]
	v_mov_b32_e32 v126, 0
	v_mov_b32_e32 v149, 0
	s_and_saveexec_b64 s[6:7], s[70:71]
	s_cbranch_execz .LBB0_533
	s_nop 0
	s_nop 0
	s_waitcnt lgkmcnt(0)
	v_sub_f32_e32 v120, v124, v7
	v_min_f32_e32 v120, 0, v120
	v_mul_f32_e32 v120, 0x3fb8aa3b, v120
	v_exp_f32_e32 v120, v120
	s_nop 0
	v_mul_f32_e32 v149, v121, v120
.LBB0_533:
	s_or_b64 exec, exec, s[6:7]
	s_and_saveexec_b64 s[6:7], s[72:73]
	s_cbranch_execz .LBB0_535
	s_nop 0
	s_waitcnt lgkmcnt(0)
	v_sub_f32_e32 v120, v124, v8
	v_min_f32_e32 v120, 0, v120
	v_mul_f32_e32 v120, 0x3fb8aa3b, v120
	v_exp_f32_e32 v120, v120
	s_nop 0
	v_mul_f32_e32 v126, v122, v120
.LBB0_535:
	s_or_b64 exec, exec, s[6:7]
	v_mov_b32_e32 v120, 0
	v_mov_b32_e32 v121, 0
	s_and_saveexec_b64 s[6:7], s[74:75]
	s_cbranch_execz .LBB0_537
	s_nop 0
	s_waitcnt lgkmcnt(0)
	v_sub_f32_e32 v121, v124, v9
	v_min_f32_e32 v121, 0, v121
	v_mul_f32_e32 v121, 0x3fb8aa3b, v121
	v_exp_f32_e32 v121, v121
	s_nop 0
	v_mul_f32_e32 v121, v123, v121
.LBB0_537:
	s_or_b64 exec, exec, s[6:7]
	v_cvt_pk_bf16_f32 v122, v127, v149
	v_cvt_pk_bf16_f32 v123, v126, v121
	ds_write_b64 v227, v[122:123] offset:62528
	ds_read_b128 v[248:251], v125 offset:30464
	s_waitcnt lgkmcnt(0)
	v_mfma_f32_16x16x32_bf16 v[108:111], v[248:251], v[108:111], 0
	ds_read_b128 v[248:251], v125 offset:30528
	s_waitcnt lgkmcnt(0)
	v_mfma_f32_16x16x32_bf16 v[108:111], v[248:251], v[112:115], v[108:111]
	ds_read_b128 v[112:115], v125 offset:30592
	s_waitcnt lgkmcnt(0)
	v_mfma_f32_16x16x32_bf16 v[104:107], v[112:115], v[104:107], v[108:111]
	s_nop 4
	ds_read_b128 v[108:111], v125 offset:30656
	s_waitcnt lgkmcnt(0)
	v_mfma_f32_16x16x32_bf16 v[104:107], v[108:111], v[116:119], v[104:107]
	s_and_saveexec_b64 s[6:7], s[76:77]
	s_cbranch_execz .LBB0_539
	s_nop 0
	s_waitcnt lgkmcnt(0)
	v_sub_f32_e32 v108, v124, v10
	v_min_f32_e32 v108, 0, v108
	v_mul_f32_e32 v108, 0x3fb8aa3b, v108
	v_exp_f32_e32 v108, v108
	s_nop 0
	v_mul_f32_e32 v120, v104, v108

; template <int PROBE, int SONLY, int CPS>
; DI void ssd_chunk_loop(const Params& p, int layer, int b, int e, int c0, f32x4 (&h)[8], float& dtot, bool write_final) {
;     ...
;           for (int r = 0; r < 4; ++r) { const int s = s0 + r; v[r] = (s <= q) ? acc[r] * __expf(fminf(aq - acs_s[s], 0.f)) : 0.f; }
.LBB0_542:
	s_nop 0
	s_waitcnt lgkmcnt(0)
	v_sub_f32_e32 v105, v124, v11
	v_min_f32_e32 v105, 0, v105
	v_mul_f32_e32 v105, 0x3fb8aa3b, v105
	v_exp_f32_e32 v105, v105
	s_nop 0
	v_mul_f32_e32 v105, v107, v105

; template <int PROBE, int SONLY, int CPS>
; DI void ssd_chunk_loop(const Params& p, int layer, int b, int e, int c0, f32x4 (&h)[8], float& dtot, bool write_final) {
;     ...
;           for (int r = 0; r < 4; ++r) { const int s = s0 + r; v[r] = (s <= q) ? acc[r] * __expf(fminf(aq - acs_s[s], 0.f)) : 0.f; }
.LBB0_553:
	s_nop 0
	s_waitcnt lgkmcnt(0)
	v_sub_f32_e32 v126, v124, v12
	v_min_f32_e32 v126, 0, v126
	v_mul_f32_e32 v126, 0x3fb8aa3b, v126
	v_exp_f32_e32 v126, v126
	s_nop 0
	v_mul_f32_e32 v149, v120, v126
	s_or_b64 exec, exec, s[6:7]
	v_mov_b32_e32 v120, 0
	s_and_saveexec_b64 s[6:7], s[54:55]
	s_cbranch_execz .LBB0_517
.LBB0_554:
	s_nop 0
	s_waitcnt lgkmcnt(0)
	v_sub_f32_e32 v120, v124, v13
	v_min_f32_e32 v120, 0, v120
	v_mul_f32_e32 v120, 0x3fb8aa3b, v120
	v_exp_f32_e32 v120, v120
	s_nop 0
	v_mul_f32_e32 v120, v121, v120
	s_or_b64 exec, exec, s[6:7]
	s_and_saveexec_b64 s[6:7], s[56:57]
	s_cbranch_execnz .LBB0_518
	s_branch .LBB0_519
.LBB0_555:
	s_nop 0
	s_waitcnt lgkmcnt(0)
	v_sub_f32_e32 v108, v124, v14
	v_min_f32_e32 v108, 0, v108
	v_mul_f32_e32 v108, 0x3fb8aa3b, v108
	v_exp_f32_e32 v108, v108
	s_nop 0
	v_mul_f32_e32 v108, v105, v108
	s_or_b64 exec, exec, s[6:7]
	s_and_saveexec_b64 s[6:7], s[80:81]
	s_cbranch_execz .LBB0_541
.LBB0_556:
	s_nop 0
	s_waitcnt lgkmcnt(0)
	v_sub_f32_e32 v104, v124, v15
	v_min_f32_e32 v104, 0, v104
	v_mul_f32_e32 v104, 0x3fb8aa3b, v104
	v_exp_f32_e32 v104, v104
	s_nop 0
	v_mul_f32_e32 v104, v106, v104
	s_or_b64 exec, exec, s[6:7]
	v_mov_b32_e32 v105, 0
	s_and_saveexec_b64 s[6:7], s[82:83]
	s_cbranch_execnz .LBB0_542
	s_branch .LBB0_543

; template <int PROBE, int SONLY, int CPS>
; DI void ssd_chunk_loop(const Params& p, int layer, int b, int e, int c0, f32x4 (&h)[8], float& dtot, bool write_final) {
;     ...
;     {
;       const int nb_ = b * 2048 + ((cc + 1 < c0 + CPS) ? (cc + 1) : cc) * 64;
; #pragma unroll
;       for (int i = 0; i < 4; ++i) {
;         const int idx = tid + 256 * i, r = idx >> 4, c16 = idx & 15;
;         if (!SONLY) pc[i] = *(const u32x4*)(XBC + (size_t)(nb_ + r) * 1280 + 1024 + g * 128 + c16 * 8);
;         pb[i] = *(const u32x4*)(XBC + (size_t)(nb_ + r) * 1280 + 768 + g * 128 + c16 * 8);
;       }
; #pragma unroll
;       for (int i = 0; i < 2; ++i) {
;         const int idx = tid + 256 * i, r = idx >> 3, c8 = idx & 7;
;         px[i] = *(const u32x4*)(XBC + (size_t)(nb_ + r) * 1280 + e * 64 + c8 * 8);
;       }
;       pru = PROJ[(size_t)(nb_ + lane) * NPAD + C_DT + e];
;     }
;     uint2 dx[4], dz[4];
;     if (!SONLY)
; #pragma unroll
;     for (int qt = 0; qt < 4; ++qt) {
;       const size_t row = (size_t)(base + qt * 16 + l15);
;       const int pcol = w * 16 + quad * 4;
;       dx[qt] = *(const uint2*)(XBC + row * 1280 + e * 64 + pcol);
;       dz[qt] = *(const uint2*)(PROJ + row * NPAD + C_Z + e * 64 + pcol);
;     }
;     __syncthreads();
;     dtot += acs_s[63];
;     if (!(PROBE & 2)) {
; #pragma unroll
;     for (int i = 0; i < 2; ++i) {
;       const int idx = tid + 256 * i, r = idx >> 3, c8 = idx & 7;
;       const float dtv = dt_s[r];
;       float f[8]; unpack8v(xr[i], f);
; #pragma unroll
;       for (int j = 0; j < 8; ++j) Xt[(c8 * 8 + j) * 72 + r] = f2bf(f[j] * dtv);
;     }
.LBB0_567:
	s_or_b64 exec, exec, s[8:9]
	s_add_i32 s8, s19, 1
	s_cmp_lt_i32 s8, s18
	s_cselect_b32 s6, s8, s19
	s_lshl_b32 s6, s6, 6
	s_add_i32 s9, s6, s2
	v_or_b32_e32 v82, s9, v142
	v_mov_b64_e32 v[80:81], s[4:5]
	v_mad_i64_i32 v[82:83], s[6:7], v82, s97, v[80:81]
	v_add_u32_e32 v136, s15, v210
	v_lshl_add_u64 v[82:83], v[100:101], 1, v[82:83]
	v_mad_i64_i32 v[86:87], s[6:7], v136, s97, v[80:81]
	v_add_co_u32_e32 v82, vcc, s16, v82
	v_lshl_add_u64 v[86:87], v[86:87], 0, s[86:87]
	v_lshlrev_b64 v[88:89], 1, v[102:103]
	v_add_u32_e32 v32, s9, v143
	v_add_u32_e32 v40, s9, v145
	v_add_u32_e32 v48, s9, v146
	v_add_u32_e32 v56, s9, v147
	v_add_u32_e32 v64, s9, v144
	v_add_u32_e32 v66, s9, v148
	v_addc_co_u32_e32 v83, vcc, 0, v83, vcc
	v_lshl_add_u64 v[86:87], v[86:87], 0, v[88:89]
	v_mad_i64_i32 v[36:37], s[6:7], v32, s34, v[116:117]
	v_mad_i64_i32 v[44:45], s[6:7], v40, s34, v[116:117]
	v_mad_i64_i32 v[52:53], s[6:7], v48, s34, v[116:117]
	v_mad_i64_i32 v[60:61], s[6:7], v56, s34, v[116:117]
	v_mad_i64_i32 v[64:65], s[6:7], v64, s34, v[98:99]
	v_mad_i64_i32 v[68:69], s[6:7], v66, s34, v[98:99]
	v_add_co_u32_e32 v86, vcc, s10, v86
	v_add_u32_e32 v130, 16, v136
	global_load_dwordx4 v[32:35], v[36:37], off offset:2048
	s_nop 0
	global_load_dwordx4 v[36:39], v[36:37], off offset:1536
	s_nop 0
	global_load_dwordx4 v[40:43], v[44:45], off offset:2048
	s_nop 0
	global_load_dwordx4 v[44:47], v[44:45], off offset:1536
	s_nop 0
	global_load_dwordx4 v[48:51], v[52:53], off offset:2048
	s_nop 0
	global_load_dwordx4 v[52:55], v[52:53], off offset:1536
	s_nop 0
	global_load_dwordx4 v[56:59], v[60:61], off offset:2048
	s_nop 0
	global_load_dwordx4 v[60:63], v[60:61], off offset:1536
	s_nop 0
	global_load_dwordx4 v[64:67], v[64:65], off
	s_nop 0
	global_load_dwordx4 v[68:71], v[68:69], off
	v_mad_i64_i32 v[84:85], s[6:7], v136, s34, v[104:105]
	v_addc_co_u32_e32 v87, vcc, 0, v87, vcc
	v_mad_i64_i32 v[90:91], s[6:7], v130, s34, v[104:105]
	global_load_ushort v163, v[82:83], off offset:1536
	global_load_dwordx2 v[140:141], v[84:85], off
	global_load_dwordx2 v[138:139], v[86:87], off offset:1536
	global_load_dwordx2 v[132:133], v[90:91], off
	v_mad_i64_i32 v[82:83], s[6:7], v130, s97, v[80:81]
	v_lshl_add_u64 v[82:83], v[82:83], 0, s[86:87]
	v_add_u32_e32 v124, 32, v136
	v_lshl_add_u64 v[82:83], v[82:83], 0, v[88:89]
	v_mad_i64_i32 v[86:87], s[6:7], v124, s97, v[80:81]
	v_add_co_u32_e32 v82, vcc, s10, v82
	v_lshl_add_u64 v[86:87], v[86:87], 0, s[86:87]
	v_add_u32_e32 v118, 48, v136
	v_addc_co_u32_e32 v83, vcc, 0, v83, vcc
	v_lshl_add_u64 v[86:87], v[86:87], 0, v[88:89]
	v_mad_i64_i32 v[80:81], s[6:7], v118, s97, v[80:81]
	v_add_co_u32_e32 v86, vcc, s10, v86
	v_lshl_add_u64 v[80:81], v[80:81], 0, s[86:87]
	s_nop 0
	v_addc_co_u32_e32 v87, vcc, 0, v87, vcc
	v_lshl_add_u64 v[80:81], v[80:81], 0, v[88:89]
	v_add_co_u32_e32 v80, vcc, s10, v80
	v_mad_i64_i32 v[84:85], s[6:7], v124, s34, v[104:105]
	s_nop 0
	v_addc_co_u32_e32 v81, vcc, 0, v81, vcc
	v_mad_i64_i32 v[90:91], s[6:7], v118, s34, v[104:105]
	global_load_dwordx2 v[134:135], v[82:83], off offset:1536
	global_load_dwordx2 v[128:129], v[84:85], off
	global_load_dwordx2 v[126:127], v[86:87], off offset:1536
	global_load_dwordx2 v[120:121], v[90:91], off
	global_load_dwordx2 v[122:123], v[80:81], off offset:1536
	s_waitcnt lgkmcnt(0)
	s_barrier
	ds_read_b32 v81, v169
	s_waitcnt vmcnt(21)
	v_lshlrev_b32_e32 v82, 16, v76
	v_and_b32_e32 v76, 0xffff0000, v76
	v_mov_b32_e32 v80, s20
	v_lshlrev_b32_e32 v83, 16, v77
	s_waitcnt lgkmcnt(0)
	v_mul_f32_e32 v76, v81, v76
	v_cvt_pk_bf16_f32 v76, v76, s0
	ds_read_b32 v80, v80
	ds_read_b32 v86, v170
	ds_read_b32 v87, v151
	ds_write_b16 v213, v76 offset:53392
	v_mul_f32_e32 v76, v81, v83
	v_and_b32_e32 v77, 0xffff0000, v77
	v_cvt_pk_bf16_f32 v76, v76, s0
	ds_write_b16 v213, v76 offset:53536
	v_mul_f32_e32 v76, v81, v77
	v_lshlrev_b32_e32 v84, 16, v78
	v_cvt_pk_bf16_f32 v76, v76, s0
	ds_write_b16 v213, v76 offset:53680
	v_mul_f32_e32 v76, v81, v84
	v_and_b32_e32 v78, 0xffff0000, v78
	v_cvt_pk_bf16_f32 v76, v76, s0
	ds_write_b16 v213, v76 offset:53824
	v_mul_f32_e32 v76, v81, v78
	v_lshlrev_b32_e32 v85, 16, v79
	v_cvt_pk_bf16_f32 v76, v76, s0
	ds_write_b16 v213, v76 offset:53968
	v_mul_f32_e32 v76, v81, v85
	v_and_b32_e32 v79, 0xffff0000, v79
	v_cvt_pk_bf16_f32 v76, v76, s0
	ds_write_b16 v213, v76 offset:54112
	v_mul_f32_e32 v76, v81, v79
	v_cvt_pk_bf16_f32 v76, v76, s0
	ds_write_b16 v213, v76 offset:54256
	s_waitcnt vmcnt(20)
	v_lshlrev_b32_e32 v76, 16, v72
	v_and_b32_e32 v72, 0xffff0000, v72
	v_mul_f32_e32 v82, v81, v82
	s_waitcnt lgkmcnt(8)
	v_mul_f32_e32 v72, v86, v72
	v_cvt_pk_bf16_f32 v82, v82, s0
	v_lshlrev_b32_e32 v77, 16, v73
	v_cvt_pk_bf16_f32 v72, v72, s0
	ds_write_b16 v213, v82 offset:53248
	ds_write_b16 v214, v72 offset:53392
	v_mul_f32_e32 v72, v86, v77
	v_and_b32_e32 v73, 0xffff0000, v73
	v_cvt_pk_bf16_f32 v72, v72, s0
	ds_write_b16 v214, v72 offset:53536
	v_mul_f32_e32 v72, v86, v73
	v_lshlrev_b32_e32 v78, 16, v74
	v_cvt_pk_bf16_f32 v72, v72, s0
	ds_write_b16 v214, v72 offset:53680
	v_mul_f32_e32 v72, v86, v78
	v_and_b32_e32 v74, 0xffff0000, v74
	v_cvt_pk_bf16_f32 v72, v72, s0
	ds_write_b16 v214, v72 offset:53824
	v_mul_f32_e32 v72, v86, v74
	v_lshlrev_b32_e32 v79, 16, v75
	v_cvt_pk_bf16_f32 v72, v72, s0
	ds_write_b16 v214, v72 offset:53968
	v_mul_f32_e32 v72, v86, v79
	v_and_b32_e32 v75, 0xffff0000, v75
	v_cvt_pk_bf16_f32 v72, v72, s0
	v_mul_f32_e32 v76, v86, v76
	ds_write_b16 v214, v72 offset:54112
	v_mul_f32_e32 v72, v86, v75
	v_cvt_pk_bf16_f32 v76, v76, s0
	v_cvt_pk_bf16_f32 v72, v72, s0
	ds_write_b16 v214, v76 offset:53248
	ds_write_b16 v214, v72 offset:54256
	v_add_u32_e32 v75, v152, v153
	s_waitcnt lgkmcnt(14)
; DI float bflo(unsigned u) { return __uint_as_float(u << 16); }
; DI float bfhi(unsigned u) { return __uint_as_float(u & 0xffff0000u); }
; DI f32x4 mfma16(bf16x8 a, bf16x8 b, f32x4 c) { return __builtin_amdgcn_mfma_f32_16x16x32_bf16(a, b, c, 0, 0, 0); }
; template <int PROBE, int SONLY, int CPS>
; DI void ssd_chunk_loop(const Params& p, int layer, int b, int e, int c0, f32x4 (&h)[8], float& dtot, bool write_final) {
;     ...
;     {
;       const int q = tid & 63, ng = tid >> 6;
;       const float dte = __expf(acs_s[63] - acs_s[q]);
; #pragma unroll
;       for (int i = 0; i < 8; ++i) {
;         const uint2 v = *(const uint2*)(Bs + q * 136 + ng * 32 + i * 4);
;         Bt2[(ng * 32 + i * 4 + 0) * 72 + q] = f2bf(bflo(v.x) * dte);
;         Bt2[(ng * 32 + i * 4 + 1) * 72 + q] = f2bf(bfhi(v.x) * dte);
;         Bt2[(ng * 32 + i * 4 + 2) * 72 + q] = f2bf(bflo(v.y) * dte);
;         Bt2[(ng * 32 + i * 4 + 3) * 72 + q] = f2bf(bfhi(v.y) * dte);
;       }
;     }
;     }
;     __syncthreads();
;     if (!(PROBE & 4) && !SONLY) {
;       const int q = w * 16 + l15;
;       const float aq = acs_s[q];
;       bf16x8 cfr[4];
; #pragma unroll
;       for (int ks = 0; ks < 4; ++ks) cfr[ks] = ldfrag(Cs, 136, w * 16, ks * 32, lane);
; #pragma unroll
;       for (int st = 0; st < 4; ++st) {
;         uint2 ov;
;         const int s0 = st * 16 + quad * 4;
;         {
;           f32x4 acc = (f32x4){0.f, 0.f, 0.f, 0.f};
; #pragma unroll
;           for (int ks = 0; ks < 4; ++ks) acc = mfma16(ldfrag(Bs, 136, st * 16, ks * 32, lane), cfr[ks], acc);
;           float v[4];
; #pragma unroll
;           for (int r = 0; r < 4; ++r) { const int s = s0 + r; v[r] = (s <= q) ? acc[r] * __expf(fminf(aq - acs_s[s], 0.f)) : 0.f; }
	v_sub_f32_e32 v74, v80, v87
	ds_read_b64 v[72:73], v75 offset:17408
	v_mul_f32_e32 v74, 0x3fb8aa3b, v74
	v_exp_f32_e32 v74, v74
	v_add_u32_e32 v93, v156, v173
	v_mov_b32_e32 v95, 0
	s_waitcnt lgkmcnt(0)
	v_lshlrev_b32_e32 v76, 16, v72
	v_and_b32_e32 v72, 0xffff0000, v72
	v_mul_f32_e32 v76, v74, v76
	v_mul_f32_e32 v72, v74, v72
	v_cvt_pk_bf16_f32 v76, v76, s0
	v_cvt_pk_bf16_f32 v72, v72, s0
	ds_write_b16 v171, v76 offset:34816
	ds_write_b16 v172, v72 offset:34960
	v_lshlrev_b32_e32 v72, 16, v73
	v_mul_f32_e32 v72, v74, v72
	v_cvt_pk_bf16_f32 v72, v72, s0
	ds_write_b16 v172, v72 offset:35104
	v_and_b32_e32 v72, 0xffff0000, v73
	v_mul_f32_e32 v72, v74, v72
	v_cvt_pk_bf16_f32 v72, v72, s0
	ds_write_b16 v172, v72 offset:35248
	ds_read_b64 v[72:73], v75 offset:17416
	v_mov_b32_e32 v119, 0
	s_waitcnt lgkmcnt(0)
	v_lshlrev_b32_e32 v76, 16, v72
	v_and_b32_e32 v72, 0xffff0000, v72
	v_mul_f32_e32 v76, v74, v76
	v_mul_f32_e32 v72, v74, v72
	v_cvt_pk_bf16_f32 v76, v76, s0
	v_cvt_pk_bf16_f32 v72, v72, s0
	ds_write_b16 v171, v76 offset:35392
	ds_write_b16 v172, v72 offset:35536
	v_lshlrev_b32_e32 v72, 16, v73
	v_mul_f32_e32 v72, v74, v72
	v_cvt_pk_bf16_f32 v72, v72, s0
	ds_write_b16 v172, v72 offset:35680
	v_and_b32_e32 v72, 0xffff0000, v73
	v_mul_f32_e32 v72, v74, v72
	v_cvt_pk_bf16_f32 v72, v72, s0
	ds_write_b16 v172, v72 offset:35824
	ds_read_b64 v[72:73], v75 offset:17424
	s_waitcnt lgkmcnt(0)
	v_lshlrev_b32_e32 v76, 16, v72
	v_and_b32_e32 v72, 0xffff0000, v72
	v_mul_f32_e32 v76, v74, v76
	v_mul_f32_e32 v72, v74, v72
	v_cvt_pk_bf16_f32 v76, v76, s0
	v_cvt_pk_bf16_f32 v72, v72, s0
	ds_write_b16 v171, v76 offset:35968
	ds_write_b16 v172, v72 offset:36112
	v_lshlrev_b32_e32 v72, 16, v73
	v_mul_f32_e32 v72, v74, v72
	v_cvt_pk_bf16_f32 v72, v72, s0
	ds_write_b16 v172, v72 offset:36256
	v_and_b32_e32 v72, 0xffff0000, v73
	v_mul_f32_e32 v72, v74, v72
	v_cvt_pk_bf16_f32 v72, v72, s0
	ds_write_b16 v172, v72 offset:36400
	ds_read_b64 v[72:73], v75 offset:17432
	s_waitcnt lgkmcnt(0)
	v_lshlrev_b32_e32 v76, 16, v72
	v_and_b32_e32 v72, 0xffff0000, v72
	v_mul_f32_e32 v76, v74, v76
	v_mul_f32_e32 v72, v74, v72
	v_cvt_pk_bf16_f32 v76, v76, s0
	v_cvt_pk_bf16_f32 v72, v72, s0
	ds_write_b16 v171, v76 offset:36544
	ds_write_b16 v172, v72 offset:36688
	v_lshlrev_b32_e32 v72, 16, v73
	v_mul_f32_e32 v72, v74, v72
	v_cvt_pk_bf16_f32 v72, v72, s0
	ds_write_b16 v172, v72 offset:36832
	v_and_b32_e32 v72, 0xffff0000, v73
	v_mul_f32_e32 v72, v74, v72
	v_cvt_pk_bf16_f32 v72, v72, s0
	ds_write_b16 v172, v72 offset:36976
	ds_read_b64 v[72:73], v75 offset:17440
	s_waitcnt lgkmcnt(0)
	v_lshlrev_b32_e32 v76, 16, v72
	v_and_b32_e32 v72, 0xffff0000, v72
	v_mul_f32_e32 v76, v74, v76
	v_mul_f32_e32 v72, v74, v72
	v_cvt_pk_bf16_f32 v76, v76, s0
	v_cvt_pk_bf16_f32 v72, v72, s0
	ds_write_b16 v171, v76 offset:37120
	ds_write_b16 v172, v72 offset:37264
	v_lshlrev_b32_e32 v72, 16, v73
	v_mul_f32_e32 v72, v74, v72
	v_cvt_pk_bf16_f32 v72, v72, s0
	ds_write_b16 v172, v72 offset:37408
	v_and_b32_e32 v72, 0xffff0000, v73
	v_mul_f32_e32 v72, v74, v72
	v_cvt_pk_bf16_f32 v72, v72, s0
	ds_write_b16 v172, v72 offset:37552
	ds_read_b64 v[72:73], v75 offset:17448
	s_waitcnt lgkmcnt(0)
	v_lshlrev_b32_e32 v76, 16, v72
	v_and_b32_e32 v72, 0xffff0000, v72
	v_mul_f32_e32 v76, v74, v76
	v_mul_f32_e32 v72, v74, v72
	v_cvt_pk_bf16_f32 v76, v76, s0
	v_cvt_pk_bf16_f32 v72, v72, s0
	ds_write_b16 v171, v76 offset:37696
	ds_write_b16 v172, v72 offset:37840
	v_lshlrev_b32_e32 v72, 16, v73
	v_mul_f32_e32 v72, v74, v72
	v_cvt_pk_bf16_f32 v72, v72, s0
	ds_write_b16 v172, v72 offset:37984
	v_and_b32_e32 v72, 0xffff0000, v73
	v_mul_f32_e32 v72, v74, v72
	v_cvt_pk_bf16_f32 v72, v72, s0
	ds_write_b16 v172, v72 offset:38128
	ds_read_b64 v[72:73], v75 offset:17456
	s_waitcnt lgkmcnt(0)
	v_lshlrev_b32_e32 v76, 16, v72
	v_and_b32_e32 v72, 0xffff0000, v72
	v_mul_f32_e32 v76, v74, v76
	v_mul_f32_e32 v72, v74, v72
	v_cvt_pk_bf16_f32 v76, v76, s0
	v_cvt_pk_bf16_f32 v72, v72, s0
	ds_write_b16 v171, v76 offset:38272
	ds_write_b16 v172, v72 offset:38416
	v_lshlrev_b32_e32 v72, 16, v73
	v_mul_f32_e32 v72, v74, v72
	v_cvt_pk_bf16_f32 v72, v72, s0
	ds_write_b16 v172, v72 offset:38560
	v_and_b32_e32 v72, 0xffff0000, v73
	v_mul_f32_e32 v72, v74, v72
	v_cvt_pk_bf16_f32 v72, v72, s0
	ds_write_b16 v172, v72 offset:38704
	ds_read_b64 v[72:73], v75 offset:17464
	s_waitcnt lgkmcnt(0)
	v_lshlrev_b32_e32 v75, 16, v72
	v_and_b32_e32 v72, 0xffff0000, v72
	v_mul_f32_e32 v75, v74, v75
	v_mul_f32_e32 v72, v74, v72
	v_cvt_pk_bf16_f32 v75, v75, s0
	v_cvt_pk_bf16_f32 v72, v72, s0
	ds_write_b16 v171, v75 offset:38848
	ds_write_b16 v172, v72 offset:38992
	v_lshlrev_b32_e32 v72, 16, v73
	v_mul_f32_e32 v72, v74, v72
	v_cvt_pk_bf16_f32 v72, v72, s0
	ds_write_b16 v172, v72 offset:39136
	v_and_b32_e32 v72, 0xffff0000, v73
	v_mul_f32_e32 v72, v74, v72
	v_cvt_pk_bf16_f32 v72, v72, s0
	ds_write_b16 v172, v72 offset:39280
	s_waitcnt lgkmcnt(0)
	s_barrier
	ds_read_b32 v224, v175
	ds_read_b32 v225, v176
	ds_read_b32 v226, v178
	ds_read_b32 v227, v179
	ds_read_b32 v228, v180
	ds_read_b32 v229, v181
	ds_read_b32 v230, v203
	ds_read_b32 v231, v204
	ds_read_b32 v232, v205
	ds_read_b32 v233, v206
	ds_read_b32 v234, v207
	ds_read_b32 v235, v211
	s_waitcnt lgkmcnt(8)
	ds_read_b32 v236, v174
	ds_read_b32 v237, v174 offset:4
	ds_read_b32 v238, v208
	ds_read_b32 v239, v160
	s_waitcnt lgkmcnt(4)
	ds_read_b128 v[72:75], v93 offset:17408
	ds_read_b128 v[76:79], v155
	ds_read_b128 v[84:87], v93 offset:17472
	s_waitcnt lgkmcnt(1)
	v_mfma_f32_16x16x32_bf16 v[88:91], v[72:75], v[76:79], 0
	ds_read_b128 v[218:221], v93 offset:17536
	ds_read_b128 v[80:83], v155 offset:64
	ds_read_b128 v[72:75], v155 offset:128
	s_waitcnt lgkmcnt(1)
	v_mfma_f32_16x16x32_bf16 v[84:87], v[84:87], v[80:83], v[88:91]
	s_nop 2
	ds_read_b128 v[88:91], v93 offset:17600
	s_waitcnt lgkmcnt(1)
	v_mfma_f32_16x16x32_bf16 v[218:221], v[218:221], v[72:75], v[84:87]
	s_nop 2
	ds_read_b128 v[84:87], v155 offset:192
	ds_read_b32 v92, v154
	s_waitcnt lgkmcnt(1)
	v_mfma_f32_16x16x32_bf16 v[88:91], v[88:91], v[84:87], v[218:221]
	s_and_saveexec_b64 s[6:7], s[52:53]
	s_cbranch_execnz .LBB0_605
	s_or_b64 exec, exec, s[6:7]
	s_nop 4
	v_mov_b32_e32 v88, 0
	s_and_saveexec_b64 s[6:7], s[54:55]
	s_cbranch_execnz .LBB0_606

; DI unsigned pack2(float a, float b) { fl2_t v = {a, b}; return __builtin_bit_cast(unsigned, __builtin_convertvector(v, bf2_t)); }
; DI f32x4 mfma16(bf16x8 a, bf16x8 b, f32x4 c) { return __builtin_amdgcn_mfma_f32_16x16x32_bf16(a, b, c, 0, 0, 0); }
; template <int PROBE, int SONLY, int CPS>
; DI void ssd_chunk_loop(const Params& p, int layer, int b, int e, int c0, f32x4 (&h)[8], float& dtot, bool write_final) {
;     ...
;       for (int st = 0; st < 4; ++st) {
;         uint2 ov;
;         const int s0 = st * 16 + quad * 4;
;         {
;           f32x4 acc = (f32x4){0.f, 0.f, 0.f, 0.f};
; #pragma unroll
;           for (int ks = 0; ks < 4; ++ks) acc = mfma16(ldfrag(Bs, 136, st * 16, ks * 32, lane), cfr[ks], acc);
;           float v[4];
; #pragma unroll
;           for (int r = 0; r < 4; ++r) { const int s = s0 + r; v[r] = (s <= q) ? acc[r] * __expf(fminf(aq - acs_s[s], 0.f)) : 0.f; }
;           ov.x = pack2(v[0], v[1]); ov.y = pack2(v[2], v[3]);
;         }
;         *(uint2*)(Ms + q * 72 + s0) = ov;
;       }
.LBB0_570:
	s_nop 0
	s_waitcnt lgkmcnt(0)
	v_sub_f32_e32 v89, v92, v224
	v_min_f32_e32 v89, 0, v89
	v_mul_f32_e32 v89, 0x3fb8aa3b, v89
	v_exp_f32_e32 v89, v89
	s_nop 0
	v_mul_f32_e32 v95, v90, v89
.LBB0_571:
	s_or_b64 exec, exec, s[6:7]
	v_mov_b32_e32 v94, 0
	v_mov_b32_e32 v89, 0
	s_and_saveexec_b64 s[6:7], s[58:59]
	s_cbranch_execz .LBB0_573
	s_nop 0
	s_waitcnt lgkmcnt(0)
	v_sub_f32_e32 v89, v92, v225
	v_min_f32_e32 v89, 0, v89
	v_mul_f32_e32 v89, 0x3fb8aa3b, v89
	v_exp_f32_e32 v89, v89
	s_nop 0
	v_mul_f32_e32 v89, v91, v89
.LBB0_573:
	s_or_b64 exec, exec, s[6:7]
	v_cvt_pk_bf16_f32 v88, v119, v88
	v_cvt_pk_bf16_f32 v89, v95, v89
	ds_write_b64 v177, v[88:89] offset:62464
	ds_read_b128 v[88:91], v93 offset:21760
	ds_read_b128 v[218:221], v93 offset:21824
	s_waitcnt lgkmcnt(1)
	v_mfma_f32_16x16x32_bf16 v[88:91], v[88:91], v[76:79], 0
	s_waitcnt lgkmcnt(0)
	v_mfma_f32_16x16x32_bf16 v[88:91], v[218:221], v[80:83], v[88:91]
	ds_read_b128 v[218:221], v93 offset:21888
	s_waitcnt lgkmcnt(0)
	v_mfma_f32_16x16x32_bf16 v[88:91], v[218:221], v[72:75], v[88:91]
	ds_read_b128 v[218:221], v93 offset:21952
	s_waitcnt lgkmcnt(0)
	v_mfma_f32_16x16x32_bf16 v[88:91], v[218:221], v[84:87], v[88:91]
	s_and_saveexec_b64 s[6:7], s[60:61]
	s_cbranch_execz .LBB0_575
	s_nop 0
	s_waitcnt lgkmcnt(0)
	v_sub_f32_e32 v94, v92, v226
	v_min_f32_e32 v94, 0, v94
	v_mul_f32_e32 v94, 0x3fb8aa3b, v94
	v_exp_f32_e32 v94, v94
	s_nop 0
	v_mul_f32_e32 v94, v88, v94
.LBB0_575:
	s_or_b64 exec, exec, s[6:7]
	s_nop 4
	v_mov_b32_e32 v88, 0
	v_mov_b32_e32 v119, 0
	s_and_saveexec_b64 s[6:7], s[62:63]
	s_cbranch_execz .LBB0_577
	s_nop 0
	s_waitcnt lgkmcnt(0)
	v_sub_f32_e32 v95, v92, v227
	v_min_f32_e32 v95, 0, v95
	v_mul_f32_e32 v95, 0x3fb8aa3b, v95
	v_exp_f32_e32 v95, v95
	s_nop 0
	v_mul_f32_e32 v119, v89, v95
.LBB0_577:
	s_or_b64 exec, exec, s[6:7]
	s_and_saveexec_b64 s[6:7], s[64:65]
	s_cbranch_execz .LBB0_579
	s_nop 0
	s_waitcnt lgkmcnt(0)
	v_sub_f32_e32 v88, v92, v228
	v_min_f32_e32 v88, 0, v88
	v_mul_f32_e32 v88, 0x3fb8aa3b, v88
	v_exp_f32_e32 v88, v88
	s_nop 0
	v_mul_f32_e32 v88, v90, v88
.LBB0_579:
	s_or_b64 exec, exec, s[6:7]
	v_mov_b32_e32 v95, 0
	v_mov_b32_e32 v89, 0
	s_and_saveexec_b64 s[6:7], s[66:67]
	s_cbranch_execz .LBB0_581
	s_nop 0
	s_waitcnt lgkmcnt(0)
	v_sub_f32_e32 v89, v92, v229
	v_min_f32_e32 v89, 0, v89
	v_mul_f32_e32 v89, 0x3fb8aa3b, v89
	v_exp_f32_e32 v89, v89
	s_nop 0
	v_mul_f32_e32 v89, v91, v89
.LBB0_581:
	s_or_b64 exec, exec, s[6:7]
	v_cvt_pk_bf16_f32 v90, v94, v119
	v_cvt_pk_bf16_f32 v91, v88, v89
	ds_write_b64 v177, v[90:91] offset:62496
	ds_read_b128 v[88:91], v93 offset:26112
	ds_read_b128 v[218:221], v93 offset:26176
	s_waitcnt lgkmcnt(1)
	v_mfma_f32_16x16x32_bf16 v[88:91], v[88:91], v[76:79], 0
	s_waitcnt lgkmcnt(0)
	v_mfma_f32_16x16x32_bf16 v[88:91], v[218:221], v[80:83], v[88:91]
	ds_read_b128 v[218:221], v93 offset:26240
	s_waitcnt lgkmcnt(0)
	v_mfma_f32_16x16x32_bf16 v[88:91], v[218:221], v[72:75], v[88:91]
	ds_read_b128 v[218:221], v93 offset:26304
	s_waitcnt lgkmcnt(0)
	v_mfma_f32_16x16x32_bf16 v[88:91], v[218:221], v[84:87], v[88:91]
	s_and_saveexec_b64 s[6:7], s[68:69]
	s_cbranch_execz .LBB0_583
	s_nop 0
	s_waitcnt lgkmcnt(0)
	v_sub_f32_e32 v94, v92, v230
	v_min_f32_e32 v94, 0, v94
	v_mul_f32_e32 v94, 0x3fb8aa3b, v94
	v_exp_f32_e32 v94, v94
	s_nop 0
	v_mul_f32_e32 v95, v88, v94
.LBB0_583:
	s_or_b64 exec, exec, s[6:7]
	v_mov_b32_e32 v94, 0
	v_mov_b32_e32 v119, 0
	s_and_saveexec_b64 s[6:7], s[70:71]
	s_cbranch_execz .LBB0_585
	s_nop 0
	s_nop 0
	s_waitcnt lgkmcnt(0)
	v_sub_f32_e32 v88, v92, v231
	v_min_f32_e32 v88, 0, v88
	v_mul_f32_e32 v88, 0x3fb8aa3b, v88
	v_exp_f32_e32 v88, v88
	s_nop 0
	v_mul_f32_e32 v119, v89, v88
.LBB0_585:
	s_or_b64 exec, exec, s[6:7]
	s_and_saveexec_b64 s[6:7], s[72:73]
	s_cbranch_execz .LBB0_587
	s_nop 0
	s_waitcnt lgkmcnt(0)
	v_sub_f32_e32 v88, v92, v232
	v_min_f32_e32 v88, 0, v88
	v_mul_f32_e32 v88, 0x3fb8aa3b, v88
	v_exp_f32_e32 v88, v88
	s_nop 0
	v_mul_f32_e32 v94, v90, v88
.LBB0_587:
	s_or_b64 exec, exec, s[6:7]
	v_mov_b32_e32 v88, 0
	v_mov_b32_e32 v89, 0
	s_and_saveexec_b64 s[6:7], s[74:75]
	s_cbranch_execz .LBB0_589
	s_nop 0
	s_waitcnt lgkmcnt(0)
	v_sub_f32_e32 v89, v92, v233
	v_min_f32_e32 v89, 0, v89
	v_mul_f32_e32 v89, 0x3fb8aa3b, v89
	v_exp_f32_e32 v89, v89
	s_nop 0
	v_mul_f32_e32 v89, v91, v89
.LBB0_589:
	s_or_b64 exec, exec, s[6:7]
	v_cvt_pk_bf16_f32 v90, v95, v119
	v_cvt_pk_bf16_f32 v91, v94, v89
	ds_write_b64 v177, v[90:91] offset:62528
	ds_read_b128 v[218:221], v93 offset:30464
	s_waitcnt lgkmcnt(0)
	v_mfma_f32_16x16x32_bf16 v[76:79], v[218:221], v[76:79], 0
	ds_read_b128 v[218:221], v93 offset:30528
	s_waitcnt lgkmcnt(0)
	v_mfma_f32_16x16x32_bf16 v[76:79], v[218:221], v[80:83], v[76:79]
	ds_read_b128 v[80:83], v93 offset:30592
	s_waitcnt lgkmcnt(0)
	v_mfma_f32_16x16x32_bf16 v[72:75], v[80:83], v[72:75], v[76:79]
	s_nop 4
	ds_read_b128 v[76:79], v93 offset:30656
	s_waitcnt lgkmcnt(0)
	v_mfma_f32_16x16x32_bf16 v[72:75], v[76:79], v[84:87], v[72:75]
	s_and_saveexec_b64 s[6:7], s[76:77]
	s_cbranch_execz .LBB0_591
	s_nop 0
	s_waitcnt lgkmcnt(0)
	v_sub_f32_e32 v76, v92, v234
	v_min_f32_e32 v76, 0, v76
	v_mul_f32_e32 v76, 0x3fb8aa3b, v76
	v_exp_f32_e32 v76, v76
	s_nop 0
	v_mul_f32_e32 v88, v72, v76

; DI unsigned pack2(float a, float b) { fl2_t v = {a, b}; return __builtin_bit_cast(unsigned, __builtin_convertvector(v, bf2_t)); }
; template <int PROBE, int SONLY, int CPS>
; DI void ssd_chunk_loop(const Params& p, int layer, int b, int e, int c0, f32x4 (&h)[8], float& dtot, bool write_final) {
;     ...
;           float v[4];
; #pragma unroll
;           for (int r = 0; r < 4; ++r) { const int s = s0 + r; v[r] = (s <= q) ? acc[r] * __expf(fminf(aq - acs_s[s], 0.f)) : 0.f; }
;           ov.x = pack2(v[0], v[1]); ov.y = pack2(v[2], v[3]);
.LBB0_594:
	s_nop 0
	s_waitcnt lgkmcnt(0)
	v_sub_f32_e32 v73, v92, v235
	v_min_f32_e32 v73, 0, v73
	v_mul_f32_e32 v73, 0x3fb8aa3b, v73
	v_exp_f32_e32 v73, v73
	s_nop 0
	v_mul_f32_e32 v73, v75, v73

; DI unsigned pack2(float a, float b) { fl2_t v = {a, b}; return __builtin_bit_cast(unsigned, __builtin_convertvector(v, bf2_t)); }
; template <int PROBE, int SONLY, int CPS>
; DI void ssd_chunk_loop(const Params& p, int layer, int b, int e, int c0, f32x4 (&h)[8], float& dtot, bool write_final) {
;     ...
;           float v[4];
; #pragma unroll
;           for (int r = 0; r < 4; ++r) { const int s = s0 + r; v[r] = (s <= q) ? acc[r] * __expf(fminf(aq - acs_s[s], 0.f)) : 0.f; }
;           ov.x = pack2(v[0], v[1]); ov.y = pack2(v[2], v[3]);
;         }
;         *(uint2*)(Ms + q * 72 + s0) = ov;
.LBB0_605:
	s_nop 0
	s_waitcnt lgkmcnt(0)
	v_sub_f32_e32 v94, v92, v236
	v_min_f32_e32 v94, 0, v94
	v_mul_f32_e32 v94, 0x3fb8aa3b, v94
	v_exp_f32_e32 v94, v94
	s_nop 0
	v_mul_f32_e32 v119, v88, v94
	s_or_b64 exec, exec, s[6:7]
	v_mov_b32_e32 v88, 0
	s_and_saveexec_b64 s[6:7], s[54:55]
	s_cbranch_execz .LBB0_569
.LBB0_606:
	s_nop 0
	s_waitcnt lgkmcnt(0)
	v_sub_f32_e32 v88, v92, v237
	v_min_f32_e32 v88, 0, v88
	v_mul_f32_e32 v88, 0x3fb8aa3b, v88
	v_exp_f32_e32 v88, v88
	s_nop 0
	v_mul_f32_e32 v88, v89, v88
	s_or_b64 exec, exec, s[6:7]
	s_and_saveexec_b64 s[6:7], s[56:57]
	s_cbranch_execnz .LBB0_570
	s_branch .LBB0_571
.LBB0_607:
	s_nop 0
	s_waitcnt lgkmcnt(0)
	v_sub_f32_e32 v76, v92, v238
	v_min_f32_e32 v76, 0, v76
	v_mul_f32_e32 v76, 0x3fb8aa3b, v76
	v_exp_f32_e32 v76, v76
	s_nop 0
	v_mul_f32_e32 v76, v73, v76
	s_or_b64 exec, exec, s[6:7]
	s_and_saveexec_b64 s[6:7], s[80:81]
	s_cbranch_execz .LBB0_593
.LBB0_608:
	s_nop 0
	s_waitcnt lgkmcnt(0)
	v_sub_f32_e32 v72, v92, v239
	v_min_f32_e32 v72, 0, v72
	v_mul_f32_e32 v72, 0x3fb8aa3b, v72
	v_exp_f32_e32 v72, v72
	s_nop 0
	v_mul_f32_e32 v72, v74, v72
	s_or_b64 exec, exec, s[6:7]
	v_mov_b32_e32 v73, 0
	s_and_saveexec_b64 s[6:7], s[82:83]
	s_cbranch_execnz .LBB0_594
	s_branch .LBB0_595

; DI void xcd_barrier(const XcdBarrier& b) {
;   asm volatile("s_waitcnt vmcnt(0)" ::: "memory");
;   __syncthreads();
;   if (threadIdx.x == 0) {
;     unsigned* bar = b.bar;
;     __builtin_amdgcn_s_waitcnt(0);
;     unsigned nloc = b.st[0], nx = b.st[1];
;     if (nloc == 0u) { xcd_barrier_complete(bar, b.x, nloc, nx); b.st[0] = nloc; b.st[1] = nx; }
.LBB0_620:
	s_nop 0
	s_nop 0
	s_nop 0
	s_nop 0
	s_nop 0
	s_nop 0
	s_nop 0
	s_nop 0
	s_nop 0
	s_nop 0
	s_nop 0
	s_nop 0
	s_nop 0
	s_nop 0
	s_nop 0
	s_nop 0
	s_waitcnt vmcnt(0)
	s_barrier
	s_mov_b64 s[0:1], exec
	v_readlane_b32 s6, v252, 1
	v_readlane_b32 s7, v252, 2
	s_and_b64 s[6:7], s[0:1], s[6:7]
	s_mov_b64 exec, s[6:7]
	s_cbranch_execz .LBB0_672
	s_waitcnt vmcnt(0) expcnt(0) lgkmcnt(0)
	ds_read_b32 v2, v161
	ds_read_b32 v0, v161 offset:4
	s_waitcnt lgkmcnt(1)
	v_cmp_ne_u32_e32 vcc, 0, v2
	s_cbranch_vccnz .LBB0_636
	s_mov_b32 s2, 1
	s_branch .LBB0_624
